# gate / ffup epilogues: image values read with ds_read_u16_d16_hi into zero-low registers (no bf16->f32 shift instructions)
# speedup vs baseline: 1.0029x; 1.0028x over previous
; DI float bf2f(u16 h) { return __uint_as_float(((unsigned)h) << 16); }
; DI float sigmoidf_(float x) { return __builtin_amdgcn_rcpf(1.f + __expf(-x)); }
; DI void img_barrier() { asm volatile("s_waitcnt lgkmcnt(0)" ::: "memory"); __builtin_amdgcn_s_barrier(); }
; DI void gate_tile(const Params& p, int l, int mt, int nt, char* smem) {
;     ...
;   EPI_IDS;
;   u16* Y = (u16*)(p.ws + O_YP) + (size_t)row0 * 3072 + col0;
;   const float* bm = p.in[26] + (size_t)l * 3072 + col0 + wc * 64 + fr;
;   img_load_bf16(Y, 3072, smem, 256, 0);
;   img_barrier();
;   u16* img = (u16*)smem + (wr * 128 + fq * 4) * IMG_LD + wc * 64 + fr;
; #pragma unroll
;   for (int n = 0; n < 4; ++n) {
;     const float bv = bm[n * 16];
; #pragma unroll
;     for (int m = 0; m < 8; ++m)
; #pragma unroll
;       for (int j = 0; j < 4; ++j) {
;         u16* q = img + (m * 16 + j) * IMG_LD + n * 16;
;         *q = f2bf(sigmoidf_(acc[m][n][j] + bv) * bf2f(*q));
;       }
;   }
.LBB0_2020:
	s_or_b64 exec, exec, s[6:7]
	s_lshl_b64 s[4:5], s[4:5], 2
	s_add_u32 s4, s12, s4
	v_and_b32_e32 v2, 0xc0, v132
	s_addc_u32 s5, s13, s5
	v_lshlrev_b32_e32 v172, 2, v2
	v_and_b32_e32 v133, 15, v132
	v_lshrrev_b32_e32 v134, 1, v132
	v_lshrrev_b32_e32 v132, 2, v132
	v_lshl_add_u64 v[0:1], s[4:5], 0, v[172:173]
	v_and_b32_e32 v132, 12, v132
	s_mov_b32 s4, 0xfffff80
	v_and_or_b32 v132, v134, s4, v132
	v_lshlrev_b32_e32 v172, 2, v133
	v_mul_lo_u32 v132, v132, s3
	v_lshl_add_u64 v[0:1], v[0:1], 0, v[172:173]
	v_add_u32_e32 v132, 16, v132
	v_lshlrev_b32_e32 v2, 1, v2
	v_lshlrev_b32_e32 v133, 1, v133
	s_waitcnt lgkmcnt(0)
	s_barrier
	v_add3_u32 v2, v132, v2, v133
	s_mov_b32 s28, 0x8000
	s_add_i32 s20, s20, 1
	s_mov_b64 s[6:7], 0
	v_mov_b32_e32 v134, 0
	v_mov_b32_e32 v135, 0
	v_mov_b32_e32 v136, 0
	v_mov_b32_e32 v137, 0
	v_mov_b32_e32 v138, 0
	v_mov_b32_e32 v139, 0
	v_mov_b32_e32 v140, 0
	v_mov_b32_e32 v141, 0
	ds_read_u16_d16_hi v134, v2
	ds_read_u16_d16_hi v135, v2 offset:528
	ds_read_u16_d16_hi v136, v2 offset:1056
	ds_read_u16_d16_hi v137, v2 offset:1584
	ds_read_u16_d16_hi v138, v2 offset:8448
	ds_read_u16_d16_hi v139, v2 offset:8976
	ds_read_u16_d16_hi v140, v2 offset:9504
	ds_read_u16_d16_hi v141, v2 offset:10032
	s_waitcnt lgkmcnt(4)
	v_mul_f32_e32 v128, v128, v134
	v_mul_f32_e32 v129, v129, v135
	v_mul_f32_e32 v130, v130, v136
	v_mul_f32_e32 v131, v131, v137
	v_cvt_pk_bf16_f32 v146, v128, v129
	v_cvt_pk_bf16_f32 v147, v130, v131
	ds_write_b16 v2, v146
	ds_write_b16_d16_hi v2, v146 offset:528
	ds_write_b16 v2, v147 offset:1056
	ds_write_b16_d16_hi v2, v147 offset:1584
	ds_read_u16_d16_hi v134, v2 offset:16896
	ds_read_u16_d16_hi v135, v2 offset:17424
	ds_read_u16_d16_hi v136, v2 offset:17952
	ds_read_u16_d16_hi v137, v2 offset:18480
	s_waitcnt lgkmcnt(8)
	v_mul_f32_e32 v124, v124, v138
	v_mul_f32_e32 v125, v125, v139
	v_mul_f32_e32 v126, v126, v140
	v_mul_f32_e32 v127, v127, v141
	v_cvt_pk_bf16_f32 v146, v124, v125
	v_cvt_pk_bf16_f32 v147, v126, v127
	ds_write_b16 v2, v146 offset:8448
	ds_write_b16_d16_hi v2, v146 offset:8976
	ds_write_b16 v2, v147 offset:9504
	ds_write_b16_d16_hi v2, v147 offset:10032
	ds_read_u16_d16_hi v138, v2 offset:25344
	ds_read_u16_d16_hi v139, v2 offset:25872
	ds_read_u16_d16_hi v140, v2 offset:26400
	ds_read_u16_d16_hi v141, v2 offset:26928
	s_waitcnt lgkmcnt(8)
	v_mul_f32_e32 v120, v120, v134
	v_mul_f32_e32 v121, v121, v135
	v_mul_f32_e32 v122, v122, v136
	v_mul_f32_e32 v123, v123, v137
	v_cvt_pk_bf16_f32 v146, v120, v121
	v_cvt_pk_bf16_f32 v147, v122, v123
	ds_write_b16 v2, v146 offset:16896
	ds_write_b16_d16_hi v2, v146 offset:17424
	ds_write_b16 v2, v147 offset:17952
	ds_write_b16_d16_hi v2, v147 offset:18480
	ds_read_u16_d16_hi v134, v2 offset:33792
	ds_read_u16_d16_hi v135, v2 offset:34320
	ds_read_u16_d16_hi v136, v2 offset:34848
	ds_read_u16_d16_hi v137, v2 offset:35376
	s_waitcnt lgkmcnt(8)
	v_mul_f32_e32 v116, v116, v138
	v_mul_f32_e32 v117, v117, v139
	v_mul_f32_e32 v118, v118, v140
	v_mul_f32_e32 v119, v119, v141
	v_cvt_pk_bf16_f32 v146, v116, v117
	v_cvt_pk_bf16_f32 v147, v118, v119
	ds_write_b16 v2, v146 offset:25344
	ds_write_b16_d16_hi v2, v146 offset:25872
	ds_write_b16 v2, v147 offset:26400
	ds_write_b16_d16_hi v2, v147 offset:26928
	ds_read_u16_d16_hi v138, v2 offset:42240
	ds_read_u16_d16_hi v139, v2 offset:42768
	ds_read_u16_d16_hi v140, v2 offset:43296
	ds_read_u16_d16_hi v141, v2 offset:43824
	s_waitcnt lgkmcnt(8)
	v_mul_f32_e32 v112, v112, v134
	v_mul_f32_e32 v113, v113, v135
	v_mul_f32_e32 v114, v114, v136
	v_mul_f32_e32 v115, v115, v137
	v_cvt_pk_bf16_f32 v146, v112, v113
	v_cvt_pk_bf16_f32 v147, v114, v115
	ds_write_b16 v2, v146 offset:33792
	ds_write_b16_d16_hi v2, v146 offset:34320
	ds_write_b16 v2, v147 offset:34848
	ds_write_b16_d16_hi v2, v147 offset:35376
	ds_read_u16_d16_hi v134, v2 offset:50688
	ds_read_u16_d16_hi v135, v2 offset:51216
	ds_read_u16_d16_hi v136, v2 offset:51744
	ds_read_u16_d16_hi v137, v2 offset:52272
	s_waitcnt lgkmcnt(8)
	v_mul_f32_e32 v108, v108, v138
	v_mul_f32_e32 v109, v109, v139
	v_mul_f32_e32 v110, v110, v140
	v_mul_f32_e32 v111, v111, v141
	v_cvt_pk_bf16_f32 v146, v108, v109
	v_cvt_pk_bf16_f32 v147, v110, v111
	ds_write_b16 v2, v146 offset:42240
	ds_write_b16_d16_hi v2, v146 offset:42768
	ds_write_b16 v2, v147 offset:43296
	ds_write_b16_d16_hi v2, v147 offset:43824
	ds_read_u16_d16_hi v138, v2 offset:59136
	ds_read_u16_d16_hi v139, v2 offset:59664
	ds_read_u16_d16_hi v140, v2 offset:60192
	ds_read_u16_d16_hi v141, v2 offset:60720
	s_waitcnt lgkmcnt(8)
	v_mul_f32_e32 v104, v104, v134
	v_mul_f32_e32 v105, v105, v135
	v_mul_f32_e32 v106, v106, v136
	v_mul_f32_e32 v107, v107, v137
	v_cvt_pk_bf16_f32 v146, v104, v105
	v_cvt_pk_bf16_f32 v147, v106, v107
	ds_write_b16 v2, v146 offset:50688
	ds_write_b16_d16_hi v2, v146 offset:51216
	ds_write_b16 v2, v147 offset:51744
	ds_write_b16_d16_hi v2, v147 offset:52272
	ds_read_u16_d16_hi v134, v2 offset:32
	ds_read_u16_d16_hi v135, v2 offset:560
	ds_read_u16_d16_hi v136, v2 offset:1088
	ds_read_u16_d16_hi v137, v2 offset:1616
	s_waitcnt lgkmcnt(8)
	v_mul_f32_e32 v100, v100, v138
	v_mul_f32_e32 v101, v101, v139
	v_mul_f32_e32 v102, v102, v140
	v_mul_f32_e32 v103, v103, v141
	v_cvt_pk_bf16_f32 v146, v100, v101
	v_cvt_pk_bf16_f32 v147, v102, v103
	ds_write_b16 v2, v146 offset:59136
	ds_write_b16_d16_hi v2, v146 offset:59664
	ds_write_b16 v2, v147 offset:60192
	ds_write_b16_d16_hi v2, v147 offset:60720
	ds_read_u16_d16_hi v138, v2 offset:8480
	ds_read_u16_d16_hi v139, v2 offset:9008
	ds_read_u16_d16_hi v140, v2 offset:9536
	ds_read_u16_d16_hi v141, v2 offset:10064
	s_waitcnt lgkmcnt(8)
; DI float bf2f(u16 h) { return __uint_as_float(((unsigned)h) << 16); }
; DI float sigmoidf_(float x) { return __builtin_amdgcn_rcpf(1.f + __expf(-x)); }
; DI void gate_tile(const Params& p, int l, int mt, int nt, char* smem) {
;     ...
;   u16* img = (u16*)smem + (wr * 128 + fq * 4) * IMG_LD + wc * 64 + fr;
; #pragma unroll
;   for (int n = 0; n < 4; ++n) {
;     const float bv = bm[n * 16];
; #pragma unroll
;     for (int m = 0; m < 8; ++m)
; #pragma unroll
;       for (int j = 0; j < 4; ++j) {
;         u16* q = img + (m * 16 + j) * IMG_LD + n * 16;
;         *q = f2bf(sigmoidf_(acc[m][n][j] + bv) * bf2f(*q));
;       }
;   }
	v_mul_f32_e32 v96, v96, v134
	v_mul_f32_e32 v97, v97, v135
	v_mul_f32_e32 v98, v98, v136
	v_mul_f32_e32 v99, v99, v137
	v_cvt_pk_bf16_f32 v146, v96, v97
	v_cvt_pk_bf16_f32 v147, v98, v99
	ds_write_b16 v2, v146 offset:32
	ds_write_b16_d16_hi v2, v146 offset:560
	ds_write_b16 v2, v147 offset:1088
	ds_write_b16_d16_hi v2, v147 offset:1616
	ds_read_u16_d16_hi v134, v2 offset:16928
	ds_read_u16_d16_hi v135, v2 offset:17456
	ds_read_u16_d16_hi v136, v2 offset:17984
	ds_read_u16_d16_hi v137, v2 offset:18512
	s_waitcnt lgkmcnt(8)
	v_mul_f32_e32 v92, v92, v138
	v_mul_f32_e32 v93, v93, v139
	v_mul_f32_e32 v94, v94, v140
	v_mul_f32_e32 v95, v95, v141
	v_cvt_pk_bf16_f32 v146, v92, v93
	v_cvt_pk_bf16_f32 v147, v94, v95
	ds_write_b16 v2, v146 offset:8480
	ds_write_b16_d16_hi v2, v146 offset:9008
	ds_write_b16 v2, v147 offset:9536
	ds_write_b16_d16_hi v2, v147 offset:10064
	ds_read_u16_d16_hi v138, v2 offset:25376
	ds_read_u16_d16_hi v139, v2 offset:25904
	ds_read_u16_d16_hi v140, v2 offset:26432
	ds_read_u16_d16_hi v141, v2 offset:26960
	s_waitcnt lgkmcnt(8)
	v_mul_f32_e32 v88, v88, v134
	v_mul_f32_e32 v89, v89, v135
	v_mul_f32_e32 v90, v90, v136
	v_mul_f32_e32 v91, v91, v137
	v_cvt_pk_bf16_f32 v146, v88, v89
	v_cvt_pk_bf16_f32 v147, v90, v91
	ds_write_b16 v2, v146 offset:16928
	ds_write_b16_d16_hi v2, v146 offset:17456
	ds_write_b16 v2, v147 offset:17984
	ds_write_b16_d16_hi v2, v147 offset:18512
	ds_read_u16_d16_hi v134, v2 offset:33824
	ds_read_u16_d16_hi v135, v2 offset:34352
	ds_read_u16_d16_hi v136, v2 offset:34880
	ds_read_u16_d16_hi v137, v2 offset:35408
	s_waitcnt lgkmcnt(8)
	v_mul_f32_e32 v84, v84, v138
	v_mul_f32_e32 v85, v85, v139
	v_mul_f32_e32 v86, v86, v140
	v_mul_f32_e32 v87, v87, v141
	v_cvt_pk_bf16_f32 v146, v84, v85
	v_cvt_pk_bf16_f32 v147, v86, v87
	ds_write_b16 v2, v146 offset:25376
	ds_write_b16_d16_hi v2, v146 offset:25904
	ds_write_b16 v2, v147 offset:26432
	ds_write_b16_d16_hi v2, v147 offset:26960
	ds_read_u16_d16_hi v138, v2 offset:42272
	ds_read_u16_d16_hi v139, v2 offset:42800
	ds_read_u16_d16_hi v140, v2 offset:43328
	ds_read_u16_d16_hi v141, v2 offset:43856
	s_waitcnt lgkmcnt(8)
	v_mul_f32_e32 v80, v80, v134
	v_mul_f32_e32 v81, v81, v135
	v_mul_f32_e32 v82, v82, v136
	v_mul_f32_e32 v83, v83, v137
	v_cvt_pk_bf16_f32 v146, v80, v81
	v_cvt_pk_bf16_f32 v147, v82, v83
	ds_write_b16 v2, v146 offset:33824
	ds_write_b16_d16_hi v2, v146 offset:34352
	ds_write_b16 v2, v147 offset:34880
	ds_write_b16_d16_hi v2, v147 offset:35408
	ds_read_u16_d16_hi v134, v2 offset:50720
	ds_read_u16_d16_hi v135, v2 offset:51248
	ds_read_u16_d16_hi v136, v2 offset:51776
	ds_read_u16_d16_hi v137, v2 offset:52304
	s_waitcnt lgkmcnt(8)
	v_mul_f32_e32 v76, v76, v138
	v_mul_f32_e32 v77, v77, v139
	v_mul_f32_e32 v78, v78, v140
	v_mul_f32_e32 v79, v79, v141
	v_cvt_pk_bf16_f32 v146, v76, v77
	v_cvt_pk_bf16_f32 v147, v78, v79
	ds_write_b16 v2, v146 offset:42272
	ds_write_b16_d16_hi v2, v146 offset:42800
	ds_write_b16 v2, v147 offset:43328
	ds_write_b16_d16_hi v2, v147 offset:43856
	ds_read_u16_d16_hi v138, v2 offset:59168
	ds_read_u16_d16_hi v139, v2 offset:59696
	ds_read_u16_d16_hi v140, v2 offset:60224
	ds_read_u16_d16_hi v141, v2 offset:60752
	s_waitcnt lgkmcnt(8)
	v_mul_f32_e32 v72, v72, v134
	v_mul_f32_e32 v73, v73, v135
	v_mul_f32_e32 v74, v74, v136
	v_mul_f32_e32 v75, v75, v137
	v_cvt_pk_bf16_f32 v146, v72, v73
	v_cvt_pk_bf16_f32 v147, v74, v75
	ds_write_b16 v2, v146 offset:50720
	ds_write_b16_d16_hi v2, v146 offset:51248
	ds_write_b16 v2, v147 offset:51776
	ds_write_b16_d16_hi v2, v147 offset:52304
	ds_read_u16_d16_hi v134, v2 offset:64
	ds_read_u16_d16_hi v135, v2 offset:592
	ds_read_u16_d16_hi v136, v2 offset:1120
	ds_read_u16_d16_hi v137, v2 offset:1648
	s_waitcnt lgkmcnt(8)
	v_mul_f32_e32 v68, v68, v138
	v_mul_f32_e32 v69, v69, v139
	v_mul_f32_e32 v70, v70, v140
	v_mul_f32_e32 v71, v71, v141
	v_cvt_pk_bf16_f32 v146, v68, v69
	v_cvt_pk_bf16_f32 v147, v70, v71
	ds_write_b16 v2, v146 offset:59168
	ds_write_b16_d16_hi v2, v146 offset:59696
	ds_write_b16 v2, v147 offset:60224
	ds_write_b16_d16_hi v2, v147 offset:60752
	ds_read_u16_d16_hi v138, v2 offset:8512
	ds_read_u16_d16_hi v139, v2 offset:9040
	ds_read_u16_d16_hi v140, v2 offset:9568
	ds_read_u16_d16_hi v141, v2 offset:10096
	s_waitcnt lgkmcnt(8)
	v_mul_f32_e32 v64, v64, v134
	v_mul_f32_e32 v65, v65, v135
	v_mul_f32_e32 v66, v66, v136
	v_mul_f32_e32 v67, v67, v137
	v_cvt_pk_bf16_f32 v146, v64, v65
	v_cvt_pk_bf16_f32 v147, v66, v67
	ds_write_b16 v2, v146 offset:64
	ds_write_b16_d16_hi v2, v146 offset:592
	ds_write_b16 v2, v147 offset:1120
	ds_write_b16_d16_hi v2, v147 offset:1648
	ds_read_u16_d16_hi v134, v2 offset:16960
	ds_read_u16_d16_hi v135, v2 offset:17488
	ds_read_u16_d16_hi v136, v2 offset:18016
	ds_read_u16_d16_hi v137, v2 offset:18544
	s_waitcnt lgkmcnt(8)
	v_mul_f32_e32 v60, v60, v138
	v_mul_f32_e32 v61, v61, v139
	v_mul_f32_e32 v62, v62, v140
	v_mul_f32_e32 v63, v63, v141
	v_cvt_pk_bf16_f32 v146, v60, v61
	v_cvt_pk_bf16_f32 v147, v62, v63
	ds_write_b16 v2, v146 offset:8512
	ds_write_b16_d16_hi v2, v146 offset:9040
	ds_write_b16 v2, v147 offset:9568
	ds_write_b16_d16_hi v2, v147 offset:10096
	ds_read_u16_d16_hi v138, v2 offset:25408
	ds_read_u16_d16_hi v139, v2 offset:25936
	ds_read_u16_d16_hi v140, v2 offset:26464
	ds_read_u16_d16_hi v141, v2 offset:26992
	s_waitcnt lgkmcnt(8)
	v_mul_f32_e32 v56, v56, v134
	v_mul_f32_e32 v57, v57, v135
	v_mul_f32_e32 v58, v58, v136
	v_mul_f32_e32 v59, v59, v137
	v_cvt_pk_bf16_f32 v146, v56, v57
	v_cvt_pk_bf16_f32 v147, v58, v59
	ds_write_b16 v2, v146 offset:16960
	ds_write_b16_d16_hi v2, v146 offset:17488
	ds_write_b16 v2, v147 offset:18016
	ds_write_b16_d16_hi v2, v147 offset:18544
	ds_read_u16_d16_hi v134, v2 offset:33856
	ds_read_u16_d16_hi v135, v2 offset:34384
	ds_read_u16_d16_hi v136, v2 offset:34912
	ds_read_u16_d16_hi v137, v2 offset:35440
	s_waitcnt lgkmcnt(8)
; DI float bf2f(u16 h) { return __uint_as_float(((unsigned)h) << 16); }
; DI float sigmoidf_(float x) { return __builtin_amdgcn_rcpf(1.f + __expf(-x)); }
; DI void gate_tile(const Params& p, int l, int mt, int nt, char* smem) {
;     ...
;   u16* img = (u16*)smem + (wr * 128 + fq * 4) * IMG_LD + wc * 64 + fr;
; #pragma unroll
;   for (int n = 0; n < 4; ++n) {
;     const float bv = bm[n * 16];
; #pragma unroll
;     for (int m = 0; m < 8; ++m)
; #pragma unroll
;       for (int j = 0; j < 4; ++j) {
;         u16* q = img + (m * 16 + j) * IMG_LD + n * 16;
;         *q = f2bf(sigmoidf_(acc[m][n][j] + bv) * bf2f(*q));
;       }
;   }
	v_mul_f32_e32 v52, v52, v138
	v_mul_f32_e32 v53, v53, v139
	v_mul_f32_e32 v54, v54, v140
	v_mul_f32_e32 v55, v55, v141
	v_cvt_pk_bf16_f32 v146, v52, v53
	v_cvt_pk_bf16_f32 v147, v54, v55
	ds_write_b16 v2, v146 offset:25408
	ds_write_b16_d16_hi v2, v146 offset:25936
	ds_write_b16 v2, v147 offset:26464
	ds_write_b16_d16_hi v2, v147 offset:26992
	ds_read_u16_d16_hi v138, v2 offset:42304
	ds_read_u16_d16_hi v139, v2 offset:42832
	ds_read_u16_d16_hi v140, v2 offset:43360
	ds_read_u16_d16_hi v141, v2 offset:43888
	s_waitcnt lgkmcnt(8)
	v_mul_f32_e32 v48, v48, v134
	v_mul_f32_e32 v49, v49, v135
	v_mul_f32_e32 v50, v50, v136
	v_mul_f32_e32 v51, v51, v137
	v_cvt_pk_bf16_f32 v146, v48, v49
	v_cvt_pk_bf16_f32 v147, v50, v51
	ds_write_b16 v2, v146 offset:33856
	ds_write_b16_d16_hi v2, v146 offset:34384
	ds_write_b16 v2, v147 offset:34912
	ds_write_b16_d16_hi v2, v147 offset:35440
	ds_read_u16_d16_hi v134, v2 offset:50752
	ds_read_u16_d16_hi v135, v2 offset:51280
	ds_read_u16_d16_hi v136, v2 offset:51808
	ds_read_u16_d16_hi v137, v2 offset:52336
	s_waitcnt lgkmcnt(8)
	v_mul_f32_e32 v44, v44, v138
	v_mul_f32_e32 v45, v45, v139
	v_mul_f32_e32 v46, v46, v140
	v_mul_f32_e32 v47, v47, v141
	v_cvt_pk_bf16_f32 v146, v44, v45
	v_cvt_pk_bf16_f32 v147, v46, v47
	ds_write_b16 v2, v146 offset:42304
	ds_write_b16_d16_hi v2, v146 offset:42832
	ds_write_b16 v2, v147 offset:43360
	ds_write_b16_d16_hi v2, v147 offset:43888
	ds_read_u16_d16_hi v138, v2 offset:59200
	ds_read_u16_d16_hi v139, v2 offset:59728
	ds_read_u16_d16_hi v140, v2 offset:60256
	ds_read_u16_d16_hi v141, v2 offset:60784
	s_waitcnt lgkmcnt(8)
	v_mul_f32_e32 v40, v40, v134
	v_mul_f32_e32 v41, v41, v135
	v_mul_f32_e32 v42, v42, v136
	v_mul_f32_e32 v43, v43, v137
	v_cvt_pk_bf16_f32 v146, v40, v41
	v_cvt_pk_bf16_f32 v147, v42, v43
	ds_write_b16 v2, v146 offset:50752
	ds_write_b16_d16_hi v2, v146 offset:51280
	ds_write_b16 v2, v147 offset:51808
	ds_write_b16_d16_hi v2, v147 offset:52336
	ds_read_u16_d16_hi v134, v2 offset:96
	ds_read_u16_d16_hi v135, v2 offset:624
	ds_read_u16_d16_hi v136, v2 offset:1152
	ds_read_u16_d16_hi v137, v2 offset:1680
	s_waitcnt lgkmcnt(8)
	v_mul_f32_e32 v36, v36, v138
	v_mul_f32_e32 v37, v37, v139
	v_mul_f32_e32 v38, v38, v140
	v_mul_f32_e32 v39, v39, v141
	v_cvt_pk_bf16_f32 v146, v36, v37
	v_cvt_pk_bf16_f32 v147, v38, v39
	ds_write_b16 v2, v146 offset:59200
	ds_write_b16_d16_hi v2, v146 offset:59728
	ds_write_b16 v2, v147 offset:60256
	ds_write_b16_d16_hi v2, v147 offset:60784
	ds_read_u16_d16_hi v138, v2 offset:8544
	ds_read_u16_d16_hi v139, v2 offset:9072
	ds_read_u16_d16_hi v140, v2 offset:9600
	ds_read_u16_d16_hi v141, v2 offset:10128
	s_waitcnt lgkmcnt(8)
	v_mul_f32_e32 v32, v32, v134
	v_mul_f32_e32 v33, v33, v135
	v_mul_f32_e32 v34, v34, v136
	v_mul_f32_e32 v35, v35, v137
	v_cvt_pk_bf16_f32 v146, v32, v33
	v_cvt_pk_bf16_f32 v147, v34, v35
	ds_write_b16 v2, v146 offset:96
	ds_write_b16_d16_hi v2, v146 offset:624
	ds_write_b16 v2, v147 offset:1152
	ds_write_b16_d16_hi v2, v147 offset:1680
	ds_read_u16_d16_hi v134, v2 offset:16992
	ds_read_u16_d16_hi v135, v2 offset:17520
	ds_read_u16_d16_hi v136, v2 offset:18048
	ds_read_u16_d16_hi v137, v2 offset:18576
	s_waitcnt lgkmcnt(8)
	v_mul_f32_e32 v28, v28, v138
	v_mul_f32_e32 v29, v29, v139
	v_mul_f32_e32 v30, v30, v140
	v_mul_f32_e32 v31, v31, v141
	v_cvt_pk_bf16_f32 v146, v28, v29
	v_cvt_pk_bf16_f32 v147, v30, v31
	ds_write_b16 v2, v146 offset:8544
	ds_write_b16_d16_hi v2, v146 offset:9072
	ds_write_b16 v2, v147 offset:9600
	ds_write_b16_d16_hi v2, v147 offset:10128
	ds_read_u16_d16_hi v138, v2 offset:25440
	ds_read_u16_d16_hi v139, v2 offset:25968
	ds_read_u16_d16_hi v140, v2 offset:26496
	ds_read_u16_d16_hi v141, v2 offset:27024
	s_waitcnt lgkmcnt(8)
	v_mul_f32_e32 v24, v24, v134
	v_mul_f32_e32 v25, v25, v135
	v_mul_f32_e32 v26, v26, v136
	v_mul_f32_e32 v27, v27, v137
	v_cvt_pk_bf16_f32 v146, v24, v25
	v_cvt_pk_bf16_f32 v147, v26, v27
	ds_write_b16 v2, v146 offset:16992
	ds_write_b16_d16_hi v2, v146 offset:17520
	ds_write_b16 v2, v147 offset:18048
	ds_write_b16_d16_hi v2, v147 offset:18576
	ds_read_u16_d16_hi v134, v2 offset:33888
	ds_read_u16_d16_hi v135, v2 offset:34416
	ds_read_u16_d16_hi v136, v2 offset:34944
	ds_read_u16_d16_hi v137, v2 offset:35472
	s_waitcnt lgkmcnt(8)
	v_mul_f32_e32 v20, v20, v138
	v_mul_f32_e32 v21, v21, v139
	v_mul_f32_e32 v22, v22, v140
	v_mul_f32_e32 v23, v23, v141
	v_cvt_pk_bf16_f32 v146, v20, v21
	v_cvt_pk_bf16_f32 v147, v22, v23
	ds_write_b16 v2, v146 offset:25440
	ds_write_b16_d16_hi v2, v146 offset:25968
	ds_write_b16 v2, v147 offset:26496
	ds_write_b16_d16_hi v2, v147 offset:27024
	ds_read_u16_d16_hi v138, v2 offset:42336
	ds_read_u16_d16_hi v139, v2 offset:42864
	ds_read_u16_d16_hi v140, v2 offset:43392
	ds_read_u16_d16_hi v141, v2 offset:43920
	s_waitcnt lgkmcnt(8)
	v_mul_f32_e32 v16, v16, v134
	v_mul_f32_e32 v17, v17, v135
	v_mul_f32_e32 v18, v18, v136
	v_mul_f32_e32 v19, v19, v137
	v_cvt_pk_bf16_f32 v146, v16, v17
	v_cvt_pk_bf16_f32 v147, v18, v19
	ds_write_b16 v2, v146 offset:33888
	ds_write_b16_d16_hi v2, v146 offset:34416
	ds_write_b16 v2, v147 offset:34944
	ds_write_b16_d16_hi v2, v147 offset:35472
	ds_read_u16_d16_hi v134, v2 offset:50784
	ds_read_u16_d16_hi v135, v2 offset:51312
	ds_read_u16_d16_hi v136, v2 offset:51840
	ds_read_u16_d16_hi v137, v2 offset:52368
	s_waitcnt lgkmcnt(8)
	v_mul_f32_e32 v12, v12, v138
	v_mul_f32_e32 v13, v13, v139
	v_mul_f32_e32 v14, v14, v140
	v_mul_f32_e32 v15, v15, v141
	v_cvt_pk_bf16_f32 v146, v12, v13
	v_cvt_pk_bf16_f32 v147, v14, v15
	ds_write_b16 v2, v146 offset:42336
	ds_write_b16_d16_hi v2, v146 offset:42864
	ds_write_b16 v2, v147 offset:43392
	ds_write_b16_d16_hi v2, v147 offset:43920
	ds_read_u16_d16_hi v138, v2 offset:59232
	ds_read_u16_d16_hi v139, v2 offset:59760
	ds_read_u16_d16_hi v140, v2 offset:60288
	ds_read_u16_d16_hi v141, v2 offset:60816
	s_waitcnt lgkmcnt(8)
	v_mul_f32_e32 v8, v8, v134
	v_mul_f32_e32 v9, v9, v135
	v_mul_f32_e32 v10, v10, v136
	v_mul_f32_e32 v11, v11, v137
	v_cvt_pk_bf16_f32 v146, v8, v9
	v_cvt_pk_bf16_f32 v147, v10, v11
	ds_write_b16 v2, v146 offset:50784
	ds_write_b16_d16_hi v2, v146 offset:51312
	ds_write_b16 v2, v147 offset:51840
	ds_write_b16_d16_hi v2, v147 offset:52368
	s_waitcnt lgkmcnt(4)
	v_mul_f32_e32 v4, v4, v138
	v_mul_f32_e32 v5, v5, v139
	v_mul_f32_e32 v6, v6, v140
	v_mul_f32_e32 v7, v7, v141
	v_cvt_pk_bf16_f32 v146, v4, v5
	v_cvt_pk_bf16_f32 v147, v6, v7
	ds_write_b16 v2, v146 offset:59232
	ds_write_b16_d16_hi v2, v146 offset:59760
	ds_write_b16 v2, v147 offset:60288
	ds_write_b16_d16_hi v2, v147 offset:60816
	v_mov_b32_e32 v1, v184
	s_waitcnt lgkmcnt(0)
	s_barrier
; DI int TID512() { int t = threadIdx.x; asm volatile("" : "+v"(t)); return t; }
; DI void img_store_bf16(u16* dst, int ld, const char* smem, int rowoff) {
;   const int tid = TID512();
; #pragma unroll
;   for (int q = 0; q < 16; ++q) {
;     const int slot = tid + q * 512, row = slot >> 5, c16 = slot & 31;
;     *(u32x4*)(dst + (size_t)row * ld + c16 * 8) = *(const u32x4*)(smem + (row + rowoff) * (IMG_LD * 2) + c16 * 16);
;   }
; }
	s_nop 0
	v_lshlrev_b32_e32 v0, 4, v1
	v_and_b32_e32 v172, 0x1f0, v0
	v_add_u32_e32 v0, 16, v172
	v_ashrrev_i32_e32 v2, 5, v1
	v_mad_u64_u32 v[4:5], s[4:5], v2, s3, v[0:1]
	ds_read_b128 v[4:7], v4
	v_lshl_add_u64 v[8:9], s[38:39], 0, v[172:173]
	v_mad_i64_i32 v[10:11], s[4:5], v2, s97, v[8:9]
	v_add_u32_e32 v2, 0x200, v1
	v_ashrrev_i32_e32 v2, 5, v2
	s_waitcnt lgkmcnt(0)
	global_store_dwordx4 v[10:11], v[4:7], off
	v_mad_i64_i32 v[10:11], s[4:5], v2, s97, v[8:9]
	s_nop 0
	v_mad_u64_u32 v[4:5], s[4:5], v2, s3, v[0:1]
	ds_read_b128 v[4:7], v4
	v_add_u32_e32 v2, 0x400, v1
	v_ashrrev_i32_e32 v2, 5, v2
	s_waitcnt lgkmcnt(0)
	global_store_dwordx4 v[10:11], v[4:7], off
	s_nop 1
	v_mad_u64_u32 v[4:5], s[4:5], v2, s3, v[0:1]
	ds_read_b128 v[4:7], v4
	v_mad_i64_i32 v[10:11], s[4:5], v2, s97, v[8:9]
	v_add_u32_e32 v2, 0x600, v1
	v_ashrrev_i32_e32 v2, 5, v2
	s_waitcnt lgkmcnt(0)
	global_store_dwordx4 v[10:11], v[4:7], off
	v_mad_i64_i32 v[10:11], s[4:5], v2, s97, v[8:9]
	s_nop 0
	v_mad_u64_u32 v[4:5], s[4:5], v2, s3, v[0:1]
	ds_read_b128 v[4:7], v4
	v_add_u32_e32 v2, 0x800, v1
	v_ashrrev_i32_e32 v2, 5, v2
	s_waitcnt lgkmcnt(0)
	global_store_dwordx4 v[10:11], v[4:7], off
	s_nop 1
	v_mad_u64_u32 v[4:5], s[4:5], v2, s3, v[0:1]
	ds_read_b128 v[4:7], v4
	v_mad_i64_i32 v[10:11], s[4:5], v2, s97, v[8:9]
	v_add_u32_e32 v2, 0xa00, v1
	v_ashrrev_i32_e32 v2, 5, v2
	s_waitcnt lgkmcnt(0)
	global_store_dwordx4 v[10:11], v[4:7], off
	v_mad_i64_i32 v[10:11], s[4:5], v2, s97, v[8:9]
	s_nop 0
	v_mad_u64_u32 v[4:5], s[4:5], v2, s3, v[0:1]
	ds_read_b128 v[4:7], v4
	v_add_u32_e32 v2, 0xc00, v1
	v_ashrrev_i32_e32 v2, 5, v2
	s_waitcnt lgkmcnt(0)
	global_store_dwordx4 v[10:11], v[4:7], off
	s_nop 1
	v_mad_u64_u32 v[4:5], s[4:5], v2, s3, v[0:1]
	ds_read_b128 v[4:7], v4
	v_mad_i64_i32 v[10:11], s[4:5], v2, s97, v[8:9]
	v_add_u32_e32 v2, 0xe00, v1
	v_ashrrev_i32_e32 v2, 5, v2
	s_waitcnt lgkmcnt(0)
	global_store_dwordx4 v[10:11], v[4:7], off
	v_mad_i64_i32 v[10:11], s[4:5], v2, s97, v[8:9]
	s_nop 0
	v_mad_u64_u32 v[4:5], s[4:5], v2, s3, v[0:1]
	ds_read_b128 v[4:7], v4
	v_add_u32_e32 v2, 0x1000, v1
	v_ashrrev_i32_e32 v2, 5, v2
	s_waitcnt lgkmcnt(0)
	global_store_dwordx4 v[10:11], v[4:7], off
	s_nop 1
	v_mad_u64_u32 v[4:5], s[4:5], v2, s3, v[0:1]
	ds_read_b128 v[4:7], v4
	v_mad_i64_i32 v[10:11], s[4:5], v2, s97, v[8:9]
	v_add_u32_e32 v2, 0x1200, v1
	v_ashrrev_i32_e32 v2, 5, v2
	s_waitcnt lgkmcnt(0)
	global_store_dwordx4 v[10:11], v[4:7], off
	v_mad_i64_i32 v[10:11], s[4:5], v2, s97, v[8:9]
	s_nop 0
	v_mad_u64_u32 v[4:5], s[4:5], v2, s3, v[0:1]
	ds_read_b128 v[4:7], v4
	v_add_u32_e32 v2, 0x1400, v1
	v_ashrrev_i32_e32 v2, 5, v2
	s_waitcnt lgkmcnt(0)
	global_store_dwordx4 v[10:11], v[4:7], off
	s_nop 1
	v_mad_u64_u32 v[4:5], s[4:5], v2, s3, v[0:1]
	ds_read_b128 v[4:7], v4
	v_mad_i64_i32 v[10:11], s[4:5], v2, s97, v[8:9]
	v_add_u32_e32 v2, 0x1600, v1
	v_ashrrev_i32_e32 v2, 5, v2
	s_waitcnt lgkmcnt(0)
	global_store_dwordx4 v[10:11], v[4:7], off
	v_mad_i64_i32 v[10:11], s[4:5], v2, s97, v[8:9]
	s_nop 0
	v_mad_u64_u32 v[4:5], s[4:5], v2, s3, v[0:1]
	ds_read_b128 v[4:7], v4
	v_add_u32_e32 v2, 0x1800, v1
	v_ashrrev_i32_e32 v2, 5, v2
	s_waitcnt lgkmcnt(0)
	global_store_dwordx4 v[10:11], v[4:7], off
	s_nop 1
	v_mad_u64_u32 v[4:5], s[4:5], v2, s3, v[0:1]
	ds_read_b128 v[4:7], v4
	v_mad_i64_i32 v[10:11], s[4:5], v2, s97, v[8:9]
	v_add_u32_e32 v2, 0x1a00, v1
	v_ashrrev_i32_e32 v2, 5, v2
	s_waitcnt lgkmcnt(0)
	global_store_dwordx4 v[10:11], v[4:7], off
	v_mad_i64_i32 v[10:11], s[4:5], v2, s97, v[8:9]
	s_nop 0
	v_mad_u64_u32 v[4:5], s[4:5], v2, s3, v[0:1]
	ds_read_b128 v[4:7], v4
	v_add_u32_e32 v2, 0x1c00, v1
	v_ashrrev_i32_e32 v2, 5, v2
	s_waitcnt lgkmcnt(0)
	global_store_dwordx4 v[10:11], v[4:7], off
	s_nop 1
	v_mad_u64_u32 v[4:5], s[4:5], v2, s3, v[0:1]
	ds_read_b128 v[4:7], v4
	v_add_u32_e32 v1, 0x1e00, v1
	v_mad_i64_i32 v[10:11], s[4:5], v2, s97, v[8:9]
	v_ashrrev_i32_e32 v2, 5, v1
	v_mad_u64_u32 v[0:1], s[4:5], v2, s3, v[0:1]
	s_waitcnt lgkmcnt(0)
	global_store_dwordx4 v[10:11], v[4:7], off
	ds_read_b128 v[4:7], v0
	v_mad_i64_i32 v[0:1], s[4:5], v2, s97, v[8:9]
	s_waitcnt lgkmcnt(0)
	global_store_dwordx4 v[0:1], v[4:7], off

; DI float bf2f(u16 h) { return __uint_as_float(((unsigned)h) << 16); }
; DI float gelu_tanh(float x) { float u = 0.7978845608028654f * (x + 0.044715f * x * x * x); return x * sigmoidf_(2.f * u); }
; DI void img_barrier() { asm volatile("s_waitcnt lgkmcnt(0)" ::: "memory"); __builtin_amdgcn_s_barrier(); }
; DI void ffup_tile(const Params& p, int l, int mt, int nt, char* smem) {
;     ...
;     const u16* GUt = (const u16*)(p.ws + O_GU) + (size_t)row0 * DFF + col0;
;     if (row0 >= 2) img_load_bf16(GUt - 2 * DFF, DFF, smem, 258, 0); else img_load_bf16(GUt, DFF, smem, 256, 2);
;     img_barrier();
;     const u16* img = (const u16*)smem + (wr * 128 + fq * 4) * IMG_LD + wc * 64 + fr;
; #pragma unroll
;     for (int n = 0; n < 4; ++n) {
;       const int col = col0 + wc * 64 + n * 16 + fr;
;       const float* cw = p.in[30] + (size_t)l * 3 * DFF + col;
;       const float w0 = cw[0], w1 = cw[DFF], w2 = cw[2 * DFF], cb = p.in[31][(size_t)l * DFF + col];
; #pragma unroll
;       for (int m = 0; m < 8; ++m) {
;         if ((m & 1) == 0) asm volatile("" ::: "memory");
;         const int t = (row0 + wr * 128 + m * 16 + fq * 4) & 8191;
;         float g[6];
; #pragma unroll
;         for (int d = 0; d < 6; ++d) { const float gv = bf2f(img[(m * 16 + d) * IMG_LD + n * 16]); g[d] = (d >= 2 || t - 2 + d >= 0) ? gv : 0.f; }
; #pragma unroll
;         for (int j = 0; j < 4; ++j) acc[m][n][j] *= gelu_tanh(cb + w0 * g[j] + w1 * g[j + 1] + w2 * g[j + 2]);
;       }
.LBB0_2354:
	v_and_b32_e32 v0, 0xc0, v132
	v_and_b32_e32 v1, 15, v132
	v_ashrrev_i32_e32 v133, 1, v132
	v_lshrrev_b32_e32 v2, 2, v132
	v_and_b32_e32 v132, 12, v2
	s_mov_b32 s5, 0xfffff80
	v_lshlrev_b32_e32 v134, 1, v0
	v_lshlrev_b32_e32 v135, 1, v1
	v_or3_b32 v0, v0, s46, v1
	v_add_u32_e32 v1, s13, v133
	s_movk_i32 s4, 0x1f80
	v_and_or_b32 v2, v133, s5, v132
	v_and_or_b32 v142, v1, s4, v132
	v_ashrrev_i32_e32 v1, 31, v0
	v_mul_lo_u32 v2, v2, s3
	v_lshlrev_b64 v[0:1], 2, v[0:1]
	v_add_u32_e32 v2, 16, v2
	v_lshl_add_u64 v[132:133], s[40:41], 0, v[0:1]
	s_movk_i32 s4, 0x2000
	v_add3_u32 v2, v2, v134, v135
	v_add_co_u32_e32 v134, vcc, s4, v132
	s_movk_i32 s4, 0x5000
	s_nop 0
	v_addc_co_u32_e32 v135, vcc, 0, v133, vcc
	v_lshl_add_u64 v[0:1], s[44:45], 0, v[0:1]
	v_add_co_u32_e32 v136, vcc, s4, v132
	s_nop 1
	v_addc_co_u32_e32 v137, vcc, 0, v133, vcc
	global_load_dword v138, v[132:133], off
	global_load_dword v139, v[134:135], off offset:3072
	global_load_dword v140, v[136:137], off offset:2048
	global_load_dword v141, v[0:1], off
	global_load_dword v150, v[132:133], off offset:64
	global_load_dword v151, v[134:135], off offset:3136
	global_load_dword v152, v[136:137], off offset:2112
	global_load_dword v153, v[0:1], off offset:64
	global_load_dword v154, v[132:133], off offset:128
	global_load_dword v155, v[134:135], off offset:3200
	global_load_dword v156, v[136:137], off offset:2176
	global_load_dword v157, v[0:1], off offset:128
	global_load_dword v158, v[132:133], off offset:192
	global_load_dword v159, v[134:135], off offset:3264
	global_load_dword v160, v[136:137], off offset:2240
	global_load_dword v161, v[0:1], off offset:192
	s_waitcnt lgkmcnt(0)
	s_barrier
	v_cmp_eq_u32_e32 vcc, 0, v142
	s_add_u32 s4, s76, s38
	v_mov_b32_e32 v176, 0x3d372713
	v_mov_b32_e32 v177, 0x3d372713
	v_mov_b32_e32 v178, 0x3f4c422a
	v_mov_b32_e32 v179, 0x3f4c422a
	v_mov_b32_e32 v180, 0xbfb8aa3b
	v_mov_b32_e32 v181, 0xbfb8aa3b
	v_mov_b32_e32 v182, 1.0
	v_mov_b32_e32 v183, 1.0
	v_mov_b32_e32 v214, 0
	v_mov_b32_e32 v215, 0
	v_mov_b32_e32 v216, 0
	v_mov_b32_e32 v217, 0
	v_mov_b32_e32 v218, 0
	v_mov_b32_e32 v219, 0
	v_mov_b32_e32 v226, 0
	v_mov_b32_e32 v227, 0
	v_mov_b32_e32 v228, 0
	v_mov_b32_e32 v229, 0
	v_mov_b32_e32 v230, 0
	v_mov_b32_e32 v231, 0
	ds_read_u16_d16_hi v214, v2
	ds_read_u16_d16_hi v215, v2 offset:528
	ds_read_u16_d16_hi v216, v2 offset:1056
	ds_read_u16_d16_hi v217, v2 offset:1584
	ds_read_u16_d16_hi v218, v2 offset:2112
	ds_read_u16_d16_hi v219, v2 offset:2640
	ds_read_u16_d16_hi v226, v2 offset:8448
	ds_read_u16_d16_hi v227, v2 offset:8976
	ds_read_u16_d16_hi v228, v2 offset:9504
	ds_read_u16_d16_hi v229, v2 offset:10032
	ds_read_u16_d16_hi v230, v2 offset:10560
	ds_read_u16_d16_hi v231, v2 offset:11088
	s_waitcnt lgkmcnt(6)
	s_waitcnt vmcnt(12)
	v_mov_b32_e32 v162, v138
	v_mov_b32_e32 v163, v138
	v_mov_b32_e32 v164, v139
	v_mov_b32_e32 v165, v139
	v_mov_b32_e32 v166, v140
	v_mov_b32_e32 v167, v140
	v_mov_b32_e32 v168, v141
	v_mov_b32_e32 v169, v141
	v_cndmask_b32_e64 v214, v214, 0, vcc
	v_cndmask_b32_e64 v215, v215, 0, vcc
	v_mov_b32_e32 v220, v215
	v_mov_b32_e32 v221, v216
	v_mov_b32_e32 v222, v217
	v_mov_b32_e32 v223, v218
	v_mov_b32_e32 v224, v219
	v_pk_fma_f32 v[238:239], v[162:163], v[214:215], v[168:169]
	v_pk_fma_f32 v[240:241], v[162:163], v[216:217], v[168:169]
	v_pk_fma_f32 v[238:239], v[164:165], v[220:221], v[238:239]
	v_pk_fma_f32 v[240:241], v[164:165], v[222:223], v[240:241]
	v_pk_fma_f32 v[238:239], v[166:167], v[216:217], v[238:239]
	v_pk_fma_f32 v[240:241], v[166:167], v[218:219], v[240:241]
	v_pk_mul_f32 v[242:243], v[176:177], v[238:239]
	v_pk_mul_f32 v[244:245], v[176:177], v[240:241]
	v_pk_mul_f32 v[242:243], v[238:239], v[242:243]
	v_pk_mul_f32 v[244:245], v[240:241], v[244:245]
	v_pk_fma_f32 v[242:243], v[238:239], v[242:243], v[238:239]
	v_pk_fma_f32 v[244:245], v[240:241], v[244:245], v[240:241]
	v_pk_mul_f32 v[242:243], v[178:179], v[242:243]
	v_pk_mul_f32 v[244:245], v[178:179], v[244:245]
	v_pk_add_f32 v[242:243], v[242:243], v[242:243]
	v_pk_add_f32 v[244:245], v[244:245], v[244:245]
	v_pk_mul_f32 v[242:243], v[180:181], v[242:243]
	v_pk_mul_f32 v[244:245], v[180:181], v[244:245]
	v_exp_f32_e32 v242, v242
	v_exp_f32_e32 v243, v243
	v_exp_f32_e32 v244, v244
	v_exp_f32_e32 v245, v245
	v_pk_add_f32 v[242:243], v[182:183], v[242:243]
	v_pk_add_f32 v[244:245], v[182:183], v[244:245]
	v_rcp_f32_e32 v242, v242
	v_rcp_f32_e32 v243, v243
	v_rcp_f32_e32 v244, v244
	v_rcp_f32_e32 v245, v245
	v_pk_mul_f32 v[238:239], v[238:239], v[242:243]
	v_pk_mul_f32 v[240:241], v[240:241], v[244:245]
	v_pk_mul_f32 v[128:129], v[128:129], v[238:239]
	v_pk_mul_f32 v[130:131], v[130:131], v[240:241]
	ds_read_u16_d16_hi v214, v2 offset:16896
	ds_read_u16_d16_hi v215, v2 offset:17424
	ds_read_u16_d16_hi v216, v2 offset:17952
	ds_read_u16_d16_hi v217, v2 offset:18480
	ds_read_u16_d16_hi v218, v2 offset:19008
	ds_read_u16_d16_hi v219, v2 offset:19536
	s_waitcnt lgkmcnt(6)
; DI float bf2f(u16 h) { return __uint_as_float(((unsigned)h) << 16); }
; DI float gelu_tanh(float x) { float u = 0.7978845608028654f * (x + 0.044715f * x * x * x); return x * sigmoidf_(2.f * u); }
; DI void ffup_tile(const Params& p, int l, int mt, int nt, char* smem) {
;     ...
; #pragma unroll
;       for (int m = 0; m < 8; ++m) {
;         if ((m & 1) == 0) asm volatile("" ::: "memory");
;         const int t = (row0 + wr * 128 + m * 16 + fq * 4) & 8191;
;         float g[6];
; #pragma unroll
;         for (int d = 0; d < 6; ++d) { const float gv = bf2f(img[(m * 16 + d) * IMG_LD + n * 16]); g[d] = (d >= 2 || t - 2 + d >= 0) ? gv : 0.f; }
; #pragma unroll
;         for (int j = 0; j < 4; ++j) acc[m][n][j] *= gelu_tanh(cb + w0 * g[j] + w1 * g[j + 1] + w2 * g[j + 2]);
;       }
	v_mov_b32_e32 v232, v227
	v_mov_b32_e32 v233, v228
	v_mov_b32_e32 v234, v229
	v_mov_b32_e32 v235, v230
	v_mov_b32_e32 v236, v231
	v_pk_fma_f32 v[238:239], v[162:163], v[226:227], v[168:169]
	v_pk_fma_f32 v[240:241], v[162:163], v[228:229], v[168:169]
	v_pk_fma_f32 v[238:239], v[164:165], v[232:233], v[238:239]
	v_pk_fma_f32 v[240:241], v[164:165], v[234:235], v[240:241]
	v_pk_fma_f32 v[238:239], v[166:167], v[228:229], v[238:239]
	v_pk_fma_f32 v[240:241], v[166:167], v[230:231], v[240:241]
	v_pk_mul_f32 v[242:243], v[176:177], v[238:239]
	v_pk_mul_f32 v[244:245], v[176:177], v[240:241]
	v_pk_mul_f32 v[242:243], v[238:239], v[242:243]
	v_pk_mul_f32 v[244:245], v[240:241], v[244:245]
	v_pk_fma_f32 v[242:243], v[238:239], v[242:243], v[238:239]
	v_pk_fma_f32 v[244:245], v[240:241], v[244:245], v[240:241]
	v_pk_mul_f32 v[242:243], v[178:179], v[242:243]
	v_pk_mul_f32 v[244:245], v[178:179], v[244:245]
	v_pk_add_f32 v[242:243], v[242:243], v[242:243]
	v_pk_add_f32 v[244:245], v[244:245], v[244:245]
	v_pk_mul_f32 v[242:243], v[180:181], v[242:243]
	v_pk_mul_f32 v[244:245], v[180:181], v[244:245]
	v_exp_f32_e32 v242, v242
	v_exp_f32_e32 v243, v243
	v_exp_f32_e32 v244, v244
	v_exp_f32_e32 v245, v245
	v_pk_add_f32 v[242:243], v[182:183], v[242:243]
	v_pk_add_f32 v[244:245], v[182:183], v[244:245]
	v_rcp_f32_e32 v242, v242
	v_rcp_f32_e32 v243, v243
	v_rcp_f32_e32 v244, v244
	v_rcp_f32_e32 v245, v245
	v_pk_mul_f32 v[238:239], v[238:239], v[242:243]
	v_pk_mul_f32 v[240:241], v[240:241], v[244:245]
	v_pk_mul_f32 v[124:125], v[124:125], v[238:239]
	v_pk_mul_f32 v[126:127], v[126:127], v[240:241]
	ds_read_u16_d16_hi v226, v2 offset:25344
	ds_read_u16_d16_hi v227, v2 offset:25872
	ds_read_u16_d16_hi v228, v2 offset:26400
	ds_read_u16_d16_hi v229, v2 offset:26928
	ds_read_u16_d16_hi v230, v2 offset:27456
	ds_read_u16_d16_hi v231, v2 offset:27984
	s_waitcnt lgkmcnt(6)
	v_mov_b32_e32 v220, v215
	v_mov_b32_e32 v221, v216
	v_mov_b32_e32 v222, v217
	v_mov_b32_e32 v223, v218
	v_mov_b32_e32 v224, v219
	v_pk_fma_f32 v[238:239], v[162:163], v[214:215], v[168:169]
	v_pk_fma_f32 v[240:241], v[162:163], v[216:217], v[168:169]
	v_pk_fma_f32 v[238:239], v[164:165], v[220:221], v[238:239]
	v_pk_fma_f32 v[240:241], v[164:165], v[222:223], v[240:241]
	v_pk_fma_f32 v[238:239], v[166:167], v[216:217], v[238:239]
	v_pk_fma_f32 v[240:241], v[166:167], v[218:219], v[240:241]
	v_pk_mul_f32 v[242:243], v[176:177], v[238:239]
	v_pk_mul_f32 v[244:245], v[176:177], v[240:241]
	v_pk_mul_f32 v[242:243], v[238:239], v[242:243]
	v_pk_mul_f32 v[244:245], v[240:241], v[244:245]
	v_pk_fma_f32 v[242:243], v[238:239], v[242:243], v[238:239]
	v_pk_fma_f32 v[244:245], v[240:241], v[244:245], v[240:241]
	v_pk_mul_f32 v[242:243], v[178:179], v[242:243]
	v_pk_mul_f32 v[244:245], v[178:179], v[244:245]
	v_pk_add_f32 v[242:243], v[242:243], v[242:243]
	v_pk_add_f32 v[244:245], v[244:245], v[244:245]
	v_pk_mul_f32 v[242:243], v[180:181], v[242:243]
	v_pk_mul_f32 v[244:245], v[180:181], v[244:245]
	v_exp_f32_e32 v242, v242
	v_exp_f32_e32 v243, v243
	v_exp_f32_e32 v244, v244
	v_exp_f32_e32 v245, v245
	v_pk_add_f32 v[242:243], v[182:183], v[242:243]
	v_pk_add_f32 v[244:245], v[182:183], v[244:245]
	v_rcp_f32_e32 v242, v242
	v_rcp_f32_e32 v243, v243
	v_rcp_f32_e32 v244, v244
	v_rcp_f32_e32 v245, v245
	v_pk_mul_f32 v[238:239], v[238:239], v[242:243]
	v_pk_mul_f32 v[240:241], v[240:241], v[244:245]
	v_pk_mul_f32 v[120:121], v[120:121], v[238:239]
	v_pk_mul_f32 v[122:123], v[122:123], v[240:241]
	ds_read_u16_d16_hi v214, v2 offset:33792
	ds_read_u16_d16_hi v215, v2 offset:34320
	ds_read_u16_d16_hi v216, v2 offset:34848
	ds_read_u16_d16_hi v217, v2 offset:35376
	ds_read_u16_d16_hi v218, v2 offset:35904
	ds_read_u16_d16_hi v219, v2 offset:36432
	s_waitcnt lgkmcnt(6)
	v_mov_b32_e32 v232, v227
	v_mov_b32_e32 v233, v228
	v_mov_b32_e32 v234, v229
	v_mov_b32_e32 v235, v230
	v_mov_b32_e32 v236, v231
	v_pk_fma_f32 v[238:239], v[162:163], v[226:227], v[168:169]
	v_pk_fma_f32 v[240:241], v[162:163], v[228:229], v[168:169]
	v_pk_fma_f32 v[238:239], v[164:165], v[232:233], v[238:239]
	v_pk_fma_f32 v[240:241], v[164:165], v[234:235], v[240:241]
	v_pk_fma_f32 v[238:239], v[166:167], v[228:229], v[238:239]
	v_pk_fma_f32 v[240:241], v[166:167], v[230:231], v[240:241]
	v_pk_mul_f32 v[242:243], v[176:177], v[238:239]
	v_pk_mul_f32 v[244:245], v[176:177], v[240:241]
	v_pk_mul_f32 v[242:243], v[238:239], v[242:243]
	v_pk_mul_f32 v[244:245], v[240:241], v[244:245]
	v_pk_fma_f32 v[242:243], v[238:239], v[242:243], v[238:239]
	v_pk_fma_f32 v[244:245], v[240:241], v[244:245], v[240:241]
	v_pk_mul_f32 v[242:243], v[178:179], v[242:243]
	v_pk_mul_f32 v[244:245], v[178:179], v[244:245]
	v_pk_add_f32 v[242:243], v[242:243], v[242:243]
	v_pk_add_f32 v[244:245], v[244:245], v[244:245]
	v_pk_mul_f32 v[242:243], v[180:181], v[242:243]
	v_pk_mul_f32 v[244:245], v[180:181], v[244:245]
	v_exp_f32_e32 v242, v242
	v_exp_f32_e32 v243, v243
	v_exp_f32_e32 v244, v244
	v_exp_f32_e32 v245, v245
	v_pk_add_f32 v[242:243], v[182:183], v[242:243]
	v_pk_add_f32 v[244:245], v[182:183], v[244:245]
	v_rcp_f32_e32 v242, v242
	v_rcp_f32_e32 v243, v243
	v_rcp_f32_e32 v244, v244
	v_rcp_f32_e32 v245, v245
	v_pk_mul_f32 v[238:239], v[238:239], v[242:243]
	v_pk_mul_f32 v[240:241], v[240:241], v[244:245]
	v_pk_mul_f32 v[116:117], v[116:117], v[238:239]
	v_pk_mul_f32 v[118:119], v[118:119], v[240:241]
	ds_read_u16_d16_hi v226, v2 offset:42240
	ds_read_u16_d16_hi v227, v2 offset:42768
	ds_read_u16_d16_hi v228, v2 offset:43296
	ds_read_u16_d16_hi v229, v2 offset:43824
	ds_read_u16_d16_hi v230, v2 offset:44352
	ds_read_u16_d16_hi v231, v2 offset:44880
	s_waitcnt lgkmcnt(6)
; DI float bf2f(u16 h) { return __uint_as_float(((unsigned)h) << 16); }
; DI float gelu_tanh(float x) { float u = 0.7978845608028654f * (x + 0.044715f * x * x * x); return x * sigmoidf_(2.f * u); }
; DI void ffup_tile(const Params& p, int l, int mt, int nt, char* smem) {
;     ...
; #pragma unroll
;       for (int m = 0; m < 8; ++m) {
;         if ((m & 1) == 0) asm volatile("" ::: "memory");
;         const int t = (row0 + wr * 128 + m * 16 + fq * 4) & 8191;
;         float g[6];
; #pragma unroll
;         for (int d = 0; d < 6; ++d) { const float gv = bf2f(img[(m * 16 + d) * IMG_LD + n * 16]); g[d] = (d >= 2 || t - 2 + d >= 0) ? gv : 0.f; }
; #pragma unroll
;         for (int j = 0; j < 4; ++j) acc[m][n][j] *= gelu_tanh(cb + w0 * g[j] + w1 * g[j + 1] + w2 * g[j + 2]);
;       }
	v_mov_b32_e32 v220, v215
	v_mov_b32_e32 v221, v216
	v_mov_b32_e32 v222, v217
	v_mov_b32_e32 v223, v218
	v_mov_b32_e32 v224, v219
	v_pk_fma_f32 v[238:239], v[162:163], v[214:215], v[168:169]
	v_pk_fma_f32 v[240:241], v[162:163], v[216:217], v[168:169]
	v_pk_fma_f32 v[238:239], v[164:165], v[220:221], v[238:239]
	v_pk_fma_f32 v[240:241], v[164:165], v[222:223], v[240:241]
	v_pk_fma_f32 v[238:239], v[166:167], v[216:217], v[238:239]
	v_pk_fma_f32 v[240:241], v[166:167], v[218:219], v[240:241]
	v_pk_mul_f32 v[242:243], v[176:177], v[238:239]
	v_pk_mul_f32 v[244:245], v[176:177], v[240:241]
	v_pk_mul_f32 v[242:243], v[238:239], v[242:243]
	v_pk_mul_f32 v[244:245], v[240:241], v[244:245]
	v_pk_fma_f32 v[242:243], v[238:239], v[242:243], v[238:239]
	v_pk_fma_f32 v[244:245], v[240:241], v[244:245], v[240:241]
	v_pk_mul_f32 v[242:243], v[178:179], v[242:243]
	v_pk_mul_f32 v[244:245], v[178:179], v[244:245]
	v_pk_add_f32 v[242:243], v[242:243], v[242:243]
	v_pk_add_f32 v[244:245], v[244:245], v[244:245]
	v_pk_mul_f32 v[242:243], v[180:181], v[242:243]
	v_pk_mul_f32 v[244:245], v[180:181], v[244:245]
	v_exp_f32_e32 v242, v242
	v_exp_f32_e32 v243, v243
	v_exp_f32_e32 v244, v244
	v_exp_f32_e32 v245, v245
	v_pk_add_f32 v[242:243], v[182:183], v[242:243]
	v_pk_add_f32 v[244:245], v[182:183], v[244:245]
	v_rcp_f32_e32 v242, v242
	v_rcp_f32_e32 v243, v243
	v_rcp_f32_e32 v244, v244
	v_rcp_f32_e32 v245, v245
	v_pk_mul_f32 v[238:239], v[238:239], v[242:243]
	v_pk_mul_f32 v[240:241], v[240:241], v[244:245]
	v_pk_mul_f32 v[112:113], v[112:113], v[238:239]
	v_pk_mul_f32 v[114:115], v[114:115], v[240:241]
	ds_read_u16_d16_hi v214, v2 offset:50688
	ds_read_u16_d16_hi v215, v2 offset:51216
	ds_read_u16_d16_hi v216, v2 offset:51744
	ds_read_u16_d16_hi v217, v2 offset:52272
	ds_read_u16_d16_hi v218, v2 offset:52800
	ds_read_u16_d16_hi v219, v2 offset:53328
	s_waitcnt lgkmcnt(6)
	v_mov_b32_e32 v232, v227
	v_mov_b32_e32 v233, v228
	v_mov_b32_e32 v234, v229
	v_mov_b32_e32 v235, v230
	v_mov_b32_e32 v236, v231
	v_pk_fma_f32 v[238:239], v[162:163], v[226:227], v[168:169]
	v_pk_fma_f32 v[240:241], v[162:163], v[228:229], v[168:169]
	v_pk_fma_f32 v[238:239], v[164:165], v[232:233], v[238:239]
	v_pk_fma_f32 v[240:241], v[164:165], v[234:235], v[240:241]
	v_pk_fma_f32 v[238:239], v[166:167], v[228:229], v[238:239]
	v_pk_fma_f32 v[240:241], v[166:167], v[230:231], v[240:241]
	v_pk_mul_f32 v[242:243], v[176:177], v[238:239]
	v_pk_mul_f32 v[244:245], v[176:177], v[240:241]
	v_pk_mul_f32 v[242:243], v[238:239], v[242:243]
	v_pk_mul_f32 v[244:245], v[240:241], v[244:245]
	v_pk_fma_f32 v[242:243], v[238:239], v[242:243], v[238:239]
	v_pk_fma_f32 v[244:245], v[240:241], v[244:245], v[240:241]
	v_pk_mul_f32 v[242:243], v[178:179], v[242:243]
	v_pk_mul_f32 v[244:245], v[178:179], v[244:245]
	v_pk_add_f32 v[242:243], v[242:243], v[242:243]
	v_pk_add_f32 v[244:245], v[244:245], v[244:245]
	v_pk_mul_f32 v[242:243], v[180:181], v[242:243]
	v_pk_mul_f32 v[244:245], v[180:181], v[244:245]
	v_exp_f32_e32 v242, v242
	v_exp_f32_e32 v243, v243
	v_exp_f32_e32 v244, v244
	v_exp_f32_e32 v245, v245
	v_pk_add_f32 v[242:243], v[182:183], v[242:243]
	v_pk_add_f32 v[244:245], v[182:183], v[244:245]
	v_rcp_f32_e32 v242, v242
	v_rcp_f32_e32 v243, v243
	v_rcp_f32_e32 v244, v244
	v_rcp_f32_e32 v245, v245
	v_pk_mul_f32 v[238:239], v[238:239], v[242:243]
	v_pk_mul_f32 v[240:241], v[240:241], v[244:245]
	v_pk_mul_f32 v[108:109], v[108:109], v[238:239]
	v_pk_mul_f32 v[110:111], v[110:111], v[240:241]
	ds_read_u16_d16_hi v226, v2 offset:59136
	ds_read_u16_d16_hi v227, v2 offset:59664
	ds_read_u16_d16_hi v228, v2 offset:60192
	ds_read_u16_d16_hi v229, v2 offset:60720
	ds_read_u16_d16_hi v230, v2 offset:61248
	ds_read_u16_d16_hi v231, v2 offset:61776
	s_waitcnt lgkmcnt(6)
	v_mov_b32_e32 v220, v215
	v_mov_b32_e32 v221, v216
	v_mov_b32_e32 v222, v217
	v_mov_b32_e32 v223, v218
	v_mov_b32_e32 v224, v219
	v_pk_fma_f32 v[238:239], v[162:163], v[214:215], v[168:169]
	v_pk_fma_f32 v[240:241], v[162:163], v[216:217], v[168:169]
	v_pk_fma_f32 v[238:239], v[164:165], v[220:221], v[238:239]
	v_pk_fma_f32 v[240:241], v[164:165], v[222:223], v[240:241]
	v_pk_fma_f32 v[238:239], v[166:167], v[216:217], v[238:239]
	v_pk_fma_f32 v[240:241], v[166:167], v[218:219], v[240:241]
	v_pk_mul_f32 v[242:243], v[176:177], v[238:239]
	v_pk_mul_f32 v[244:245], v[176:177], v[240:241]
	v_pk_mul_f32 v[242:243], v[238:239], v[242:243]
	v_pk_mul_f32 v[244:245], v[240:241], v[244:245]
	v_pk_fma_f32 v[242:243], v[238:239], v[242:243], v[238:239]
	v_pk_fma_f32 v[244:245], v[240:241], v[244:245], v[240:241]
	v_pk_mul_f32 v[242:243], v[178:179], v[242:243]
	v_pk_mul_f32 v[244:245], v[178:179], v[244:245]
	v_pk_add_f32 v[242:243], v[242:243], v[242:243]
	v_pk_add_f32 v[244:245], v[244:245], v[244:245]
	v_pk_mul_f32 v[242:243], v[180:181], v[242:243]
	v_pk_mul_f32 v[244:245], v[180:181], v[244:245]
	v_exp_f32_e32 v242, v242
	v_exp_f32_e32 v243, v243
	v_exp_f32_e32 v244, v244
	v_exp_f32_e32 v245, v245
	v_pk_add_f32 v[242:243], v[182:183], v[242:243]
	v_pk_add_f32 v[244:245], v[182:183], v[244:245]
	v_rcp_f32_e32 v242, v242
	v_rcp_f32_e32 v243, v243
	v_rcp_f32_e32 v244, v244
	v_rcp_f32_e32 v245, v245
	v_pk_mul_f32 v[238:239], v[238:239], v[242:243]
	v_pk_mul_f32 v[240:241], v[240:241], v[244:245]
	v_pk_mul_f32 v[104:105], v[104:105], v[238:239]
	v_pk_mul_f32 v[106:107], v[106:107], v[240:241]
	ds_read_u16_d16_hi v214, v2 offset:32
	ds_read_u16_d16_hi v215, v2 offset:560
	ds_read_u16_d16_hi v216, v2 offset:1088
	ds_read_u16_d16_hi v217, v2 offset:1616
	ds_read_u16_d16_hi v218, v2 offset:2144
	ds_read_u16_d16_hi v219, v2 offset:2672
	s_waitcnt lgkmcnt(6)
; DI float bf2f(u16 h) { return __uint_as_float(((unsigned)h) << 16); }
; DI float gelu_tanh(float x) { float u = 0.7978845608028654f * (x + 0.044715f * x * x * x); return x * sigmoidf_(2.f * u); }
; DI void ffup_tile(const Params& p, int l, int mt, int nt, char* smem) {
;     ...
;     for (int n = 0; n < 4; ++n) {
;       const int col = col0 + wc * 64 + n * 16 + fr;
;       const float* cw = p.in[30] + (size_t)l * 3 * DFF + col;
;       const float w0 = cw[0], w1 = cw[DFF], w2 = cw[2 * DFF], cb = p.in[31][(size_t)l * DFF + col];
; #pragma unroll
;       for (int m = 0; m < 8; ++m) {
;         if ((m & 1) == 0) asm volatile("" ::: "memory");
;         const int t = (row0 + wr * 128 + m * 16 + fq * 4) & 8191;
;         float g[6];
; #pragma unroll
;         for (int d = 0; d < 6; ++d) { const float gv = bf2f(img[(m * 16 + d) * IMG_LD + n * 16]); g[d] = (d >= 2 || t - 2 + d >= 0) ? gv : 0.f; }
; #pragma unroll
;         for (int j = 0; j < 4; ++j) acc[m][n][j] *= gelu_tanh(cb + w0 * g[j] + w1 * g[j + 1] + w2 * g[j + 2]);
;       }
	v_mov_b32_e32 v232, v227
	v_mov_b32_e32 v233, v228
	v_mov_b32_e32 v234, v229
	v_mov_b32_e32 v235, v230
	v_mov_b32_e32 v236, v231
	v_pk_fma_f32 v[238:239], v[162:163], v[226:227], v[168:169]
	v_pk_fma_f32 v[240:241], v[162:163], v[228:229], v[168:169]
	v_pk_fma_f32 v[238:239], v[164:165], v[232:233], v[238:239]
	v_pk_fma_f32 v[240:241], v[164:165], v[234:235], v[240:241]
	v_pk_fma_f32 v[238:239], v[166:167], v[228:229], v[238:239]
	v_pk_fma_f32 v[240:241], v[166:167], v[230:231], v[240:241]
	v_pk_mul_f32 v[242:243], v[176:177], v[238:239]
	v_pk_mul_f32 v[244:245], v[176:177], v[240:241]
	v_pk_mul_f32 v[242:243], v[238:239], v[242:243]
	v_pk_mul_f32 v[244:245], v[240:241], v[244:245]
	v_pk_fma_f32 v[242:243], v[238:239], v[242:243], v[238:239]
	v_pk_fma_f32 v[244:245], v[240:241], v[244:245], v[240:241]
	v_pk_mul_f32 v[242:243], v[178:179], v[242:243]
	v_pk_mul_f32 v[244:245], v[178:179], v[244:245]
	v_pk_add_f32 v[242:243], v[242:243], v[242:243]
	v_pk_add_f32 v[244:245], v[244:245], v[244:245]
	v_pk_mul_f32 v[242:243], v[180:181], v[242:243]
	v_pk_mul_f32 v[244:245], v[180:181], v[244:245]
	v_exp_f32_e32 v242, v242
	v_exp_f32_e32 v243, v243
	v_exp_f32_e32 v244, v244
	v_exp_f32_e32 v245, v245
	v_pk_add_f32 v[242:243], v[182:183], v[242:243]
	v_pk_add_f32 v[244:245], v[182:183], v[244:245]
	v_rcp_f32_e32 v242, v242
	v_rcp_f32_e32 v243, v243
	v_rcp_f32_e32 v244, v244
	v_rcp_f32_e32 v245, v245
	v_pk_mul_f32 v[238:239], v[238:239], v[242:243]
	v_pk_mul_f32 v[240:241], v[240:241], v[244:245]
	v_pk_mul_f32 v[100:101], v[100:101], v[238:239]
	v_pk_mul_f32 v[102:103], v[102:103], v[240:241]
	ds_read_u16_d16_hi v226, v2 offset:8480
	ds_read_u16_d16_hi v227, v2 offset:9008
	ds_read_u16_d16_hi v228, v2 offset:9536
	ds_read_u16_d16_hi v229, v2 offset:10064
	ds_read_u16_d16_hi v230, v2 offset:10592
	ds_read_u16_d16_hi v231, v2 offset:11120
	s_waitcnt lgkmcnt(6)
	s_waitcnt vmcnt(8)
	v_mov_b32_e32 v162, v150
	v_mov_b32_e32 v163, v150
	v_mov_b32_e32 v164, v151
	v_mov_b32_e32 v165, v151
	v_mov_b32_e32 v166, v152
	v_mov_b32_e32 v167, v152
	v_mov_b32_e32 v168, v153
	v_mov_b32_e32 v169, v153
	v_cndmask_b32_e64 v214, v214, 0, vcc
	v_cndmask_b32_e64 v215, v215, 0, vcc
	v_mov_b32_e32 v220, v215
	v_mov_b32_e32 v221, v216
	v_mov_b32_e32 v222, v217
	v_mov_b32_e32 v223, v218
	v_mov_b32_e32 v224, v219
	v_pk_fma_f32 v[238:239], v[162:163], v[214:215], v[168:169]
	v_pk_fma_f32 v[240:241], v[162:163], v[216:217], v[168:169]
	v_pk_fma_f32 v[238:239], v[164:165], v[220:221], v[238:239]
	v_pk_fma_f32 v[240:241], v[164:165], v[222:223], v[240:241]
	v_pk_fma_f32 v[238:239], v[166:167], v[216:217], v[238:239]
	v_pk_fma_f32 v[240:241], v[166:167], v[218:219], v[240:241]
	v_pk_mul_f32 v[242:243], v[176:177], v[238:239]
	v_pk_mul_f32 v[244:245], v[176:177], v[240:241]
	v_pk_mul_f32 v[242:243], v[238:239], v[242:243]
	v_pk_mul_f32 v[244:245], v[240:241], v[244:245]
	v_pk_fma_f32 v[242:243], v[238:239], v[242:243], v[238:239]
	v_pk_fma_f32 v[244:245], v[240:241], v[244:245], v[240:241]
	v_pk_mul_f32 v[242:243], v[178:179], v[242:243]
	v_pk_mul_f32 v[244:245], v[178:179], v[244:245]
	v_pk_add_f32 v[242:243], v[242:243], v[242:243]
	v_pk_add_f32 v[244:245], v[244:245], v[244:245]
	v_pk_mul_f32 v[242:243], v[180:181], v[242:243]
	v_pk_mul_f32 v[244:245], v[180:181], v[244:245]
	v_exp_f32_e32 v242, v242
	v_exp_f32_e32 v243, v243
	v_exp_f32_e32 v244, v244
	v_exp_f32_e32 v245, v245
	v_pk_add_f32 v[242:243], v[182:183], v[242:243]
	v_pk_add_f32 v[244:245], v[182:183], v[244:245]
	v_rcp_f32_e32 v242, v242
	v_rcp_f32_e32 v243, v243
	v_rcp_f32_e32 v244, v244
	v_rcp_f32_e32 v245, v245
	v_pk_mul_f32 v[238:239], v[238:239], v[242:243]
	v_pk_mul_f32 v[240:241], v[240:241], v[244:245]
	v_pk_mul_f32 v[96:97], v[96:97], v[238:239]
	v_pk_mul_f32 v[98:99], v[98:99], v[240:241]
	ds_read_u16_d16_hi v214, v2 offset:16928
	ds_read_u16_d16_hi v215, v2 offset:17456
	ds_read_u16_d16_hi v216, v2 offset:17984
	ds_read_u16_d16_hi v217, v2 offset:18512
	ds_read_u16_d16_hi v218, v2 offset:19040
	ds_read_u16_d16_hi v219, v2 offset:19568
	s_waitcnt lgkmcnt(6)
	v_mov_b32_e32 v232, v227
	v_mov_b32_e32 v233, v228
	v_mov_b32_e32 v234, v229
	v_mov_b32_e32 v235, v230
	v_mov_b32_e32 v236, v231
	v_pk_fma_f32 v[238:239], v[162:163], v[226:227], v[168:169]
	v_pk_fma_f32 v[240:241], v[162:163], v[228:229], v[168:169]
	v_pk_fma_f32 v[238:239], v[164:165], v[232:233], v[238:239]
	v_pk_fma_f32 v[240:241], v[164:165], v[234:235], v[240:241]
	v_pk_fma_f32 v[238:239], v[166:167], v[228:229], v[238:239]
	v_pk_fma_f32 v[240:241], v[166:167], v[230:231], v[240:241]
	v_pk_mul_f32 v[242:243], v[176:177], v[238:239]
	v_pk_mul_f32 v[244:245], v[176:177], v[240:241]
	v_pk_mul_f32 v[242:243], v[238:239], v[242:243]
	v_pk_mul_f32 v[244:245], v[240:241], v[244:245]
	v_pk_fma_f32 v[242:243], v[238:239], v[242:243], v[238:239]
	v_pk_fma_f32 v[244:245], v[240:241], v[244:245], v[240:241]
	v_pk_mul_f32 v[242:243], v[178:179], v[242:243]
	v_pk_mul_f32 v[244:245], v[178:179], v[244:245]
	v_pk_add_f32 v[242:243], v[242:243], v[242:243]
	v_pk_add_f32 v[244:245], v[244:245], v[244:245]
	v_pk_mul_f32 v[242:243], v[180:181], v[242:243]
	v_pk_mul_f32 v[244:245], v[180:181], v[244:245]
	v_exp_f32_e32 v242, v242
	v_exp_f32_e32 v243, v243
	v_exp_f32_e32 v244, v244
	v_exp_f32_e32 v245, v245
	v_pk_add_f32 v[242:243], v[182:183], v[242:243]
	v_pk_add_f32 v[244:245], v[182:183], v[244:245]
	v_rcp_f32_e32 v242, v242
	v_rcp_f32_e32 v243, v243
	v_rcp_f32_e32 v244, v244
	v_rcp_f32_e32 v245, v245
	v_pk_mul_f32 v[238:239], v[238:239], v[242:243]
	v_pk_mul_f32 v[240:241], v[240:241], v[244:245]
	v_pk_mul_f32 v[92:93], v[92:93], v[238:239]
	v_pk_mul_f32 v[94:95], v[94:95], v[240:241]
	ds_read_u16_d16_hi v226, v2 offset:25376
	ds_read_u16_d16_hi v227, v2 offset:25904
	ds_read_u16_d16_hi v228, v2 offset:26432
	ds_read_u16_d16_hi v229, v2 offset:26960
	ds_read_u16_d16_hi v230, v2 offset:27488
	ds_read_u16_d16_hi v231, v2 offset:28016
	s_waitcnt lgkmcnt(6)
; DI float bf2f(u16 h) { return __uint_as_float(((unsigned)h) << 16); }
; DI float gelu_tanh(float x) { float u = 0.7978845608028654f * (x + 0.044715f * x * x * x); return x * sigmoidf_(2.f * u); }
; DI void ffup_tile(const Params& p, int l, int mt, int nt, char* smem) {
;     ...
; #pragma unroll
;       for (int m = 0; m < 8; ++m) {
;         if ((m & 1) == 0) asm volatile("" ::: "memory");
;         const int t = (row0 + wr * 128 + m * 16 + fq * 4) & 8191;
;         float g[6];
; #pragma unroll
;         for (int d = 0; d < 6; ++d) { const float gv = bf2f(img[(m * 16 + d) * IMG_LD + n * 16]); g[d] = (d >= 2 || t - 2 + d >= 0) ? gv : 0.f; }
; #pragma unroll
;         for (int j = 0; j < 4; ++j) acc[m][n][j] *= gelu_tanh(cb + w0 * g[j] + w1 * g[j + 1] + w2 * g[j + 2]);
;       }
	v_mov_b32_e32 v220, v215
	v_mov_b32_e32 v221, v216
	v_mov_b32_e32 v222, v217
	v_mov_b32_e32 v223, v218
	v_mov_b32_e32 v224, v219
	v_pk_fma_f32 v[238:239], v[162:163], v[214:215], v[168:169]
	v_pk_fma_f32 v[240:241], v[162:163], v[216:217], v[168:169]
	v_pk_fma_f32 v[238:239], v[164:165], v[220:221], v[238:239]
	v_pk_fma_f32 v[240:241], v[164:165], v[222:223], v[240:241]
	v_pk_fma_f32 v[238:239], v[166:167], v[216:217], v[238:239]
	v_pk_fma_f32 v[240:241], v[166:167], v[218:219], v[240:241]
	v_pk_mul_f32 v[242:243], v[176:177], v[238:239]
	v_pk_mul_f32 v[244:245], v[176:177], v[240:241]
	v_pk_mul_f32 v[242:243], v[238:239], v[242:243]
	v_pk_mul_f32 v[244:245], v[240:241], v[244:245]
	v_pk_fma_f32 v[242:243], v[238:239], v[242:243], v[238:239]
	v_pk_fma_f32 v[244:245], v[240:241], v[244:245], v[240:241]
	v_pk_mul_f32 v[242:243], v[178:179], v[242:243]
	v_pk_mul_f32 v[244:245], v[178:179], v[244:245]
	v_pk_add_f32 v[242:243], v[242:243], v[242:243]
	v_pk_add_f32 v[244:245], v[244:245], v[244:245]
	v_pk_mul_f32 v[242:243], v[180:181], v[242:243]
	v_pk_mul_f32 v[244:245], v[180:181], v[244:245]
	v_exp_f32_e32 v242, v242
	v_exp_f32_e32 v243, v243
	v_exp_f32_e32 v244, v244
	v_exp_f32_e32 v245, v245
	v_pk_add_f32 v[242:243], v[182:183], v[242:243]
	v_pk_add_f32 v[244:245], v[182:183], v[244:245]
	v_rcp_f32_e32 v242, v242
	v_rcp_f32_e32 v243, v243
	v_rcp_f32_e32 v244, v244
	v_rcp_f32_e32 v245, v245
	v_pk_mul_f32 v[238:239], v[238:239], v[242:243]
	v_pk_mul_f32 v[240:241], v[240:241], v[244:245]
	v_pk_mul_f32 v[88:89], v[88:89], v[238:239]
	v_pk_mul_f32 v[90:91], v[90:91], v[240:241]
	ds_read_u16_d16_hi v214, v2 offset:33824
	ds_read_u16_d16_hi v215, v2 offset:34352
	ds_read_u16_d16_hi v216, v2 offset:34880
	ds_read_u16_d16_hi v217, v2 offset:35408
	ds_read_u16_d16_hi v218, v2 offset:35936
	ds_read_u16_d16_hi v219, v2 offset:36464
	s_waitcnt lgkmcnt(6)
	v_mov_b32_e32 v232, v227
	v_mov_b32_e32 v233, v228
	v_mov_b32_e32 v234, v229
	v_mov_b32_e32 v235, v230
	v_mov_b32_e32 v236, v231
	v_pk_fma_f32 v[238:239], v[162:163], v[226:227], v[168:169]
	v_pk_fma_f32 v[240:241], v[162:163], v[228:229], v[168:169]
	v_pk_fma_f32 v[238:239], v[164:165], v[232:233], v[238:239]
	v_pk_fma_f32 v[240:241], v[164:165], v[234:235], v[240:241]
	v_pk_fma_f32 v[238:239], v[166:167], v[228:229], v[238:239]
	v_pk_fma_f32 v[240:241], v[166:167], v[230:231], v[240:241]
	v_pk_mul_f32 v[242:243], v[176:177], v[238:239]
	v_pk_mul_f32 v[244:245], v[176:177], v[240:241]
	v_pk_mul_f32 v[242:243], v[238:239], v[242:243]
	v_pk_mul_f32 v[244:245], v[240:241], v[244:245]
	v_pk_fma_f32 v[242:243], v[238:239], v[242:243], v[238:239]
	v_pk_fma_f32 v[244:245], v[240:241], v[244:245], v[240:241]
	v_pk_mul_f32 v[242:243], v[178:179], v[242:243]
	v_pk_mul_f32 v[244:245], v[178:179], v[244:245]
	v_pk_add_f32 v[242:243], v[242:243], v[242:243]
	v_pk_add_f32 v[244:245], v[244:245], v[244:245]
	v_pk_mul_f32 v[242:243], v[180:181], v[242:243]
	v_pk_mul_f32 v[244:245], v[180:181], v[244:245]
	v_exp_f32_e32 v242, v242
	v_exp_f32_e32 v243, v243
	v_exp_f32_e32 v244, v244
	v_exp_f32_e32 v245, v245
	v_pk_add_f32 v[242:243], v[182:183], v[242:243]
	v_pk_add_f32 v[244:245], v[182:183], v[244:245]
	v_rcp_f32_e32 v242, v242
	v_rcp_f32_e32 v243, v243
	v_rcp_f32_e32 v244, v244
	v_rcp_f32_e32 v245, v245
	v_pk_mul_f32 v[238:239], v[238:239], v[242:243]
	v_pk_mul_f32 v[240:241], v[240:241], v[244:245]
	v_pk_mul_f32 v[84:85], v[84:85], v[238:239]
	v_pk_mul_f32 v[86:87], v[86:87], v[240:241]
	ds_read_u16_d16_hi v226, v2 offset:42272
	ds_read_u16_d16_hi v227, v2 offset:42800
	ds_read_u16_d16_hi v228, v2 offset:43328
	ds_read_u16_d16_hi v229, v2 offset:43856
	ds_read_u16_d16_hi v230, v2 offset:44384
	ds_read_u16_d16_hi v231, v2 offset:44912
	s_waitcnt lgkmcnt(6)
	v_mov_b32_e32 v220, v215
	v_mov_b32_e32 v221, v216
	v_mov_b32_e32 v222, v217
	v_mov_b32_e32 v223, v218
	v_mov_b32_e32 v224, v219
	v_pk_fma_f32 v[238:239], v[162:163], v[214:215], v[168:169]
	v_pk_fma_f32 v[240:241], v[162:163], v[216:217], v[168:169]
	v_pk_fma_f32 v[238:239], v[164:165], v[220:221], v[238:239]
	v_pk_fma_f32 v[240:241], v[164:165], v[222:223], v[240:241]
	v_pk_fma_f32 v[238:239], v[166:167], v[216:217], v[238:239]
	v_pk_fma_f32 v[240:241], v[166:167], v[218:219], v[240:241]
	v_pk_mul_f32 v[242:243], v[176:177], v[238:239]
	v_pk_mul_f32 v[244:245], v[176:177], v[240:241]
	v_pk_mul_f32 v[242:243], v[238:239], v[242:243]
	v_pk_mul_f32 v[244:245], v[240:241], v[244:245]
	v_pk_fma_f32 v[242:243], v[238:239], v[242:243], v[238:239]
	v_pk_fma_f32 v[244:245], v[240:241], v[244:245], v[240:241]
	v_pk_mul_f32 v[242:243], v[178:179], v[242:243]
	v_pk_mul_f32 v[244:245], v[178:179], v[244:245]
	v_pk_add_f32 v[242:243], v[242:243], v[242:243]
	v_pk_add_f32 v[244:245], v[244:245], v[244:245]
	v_pk_mul_f32 v[242:243], v[180:181], v[242:243]
	v_pk_mul_f32 v[244:245], v[180:181], v[244:245]
	v_exp_f32_e32 v242, v242
	v_exp_f32_e32 v243, v243
	v_exp_f32_e32 v244, v244
	v_exp_f32_e32 v245, v245
	v_pk_add_f32 v[242:243], v[182:183], v[242:243]
	v_pk_add_f32 v[244:245], v[182:183], v[244:245]
	v_rcp_f32_e32 v242, v242
	v_rcp_f32_e32 v243, v243
	v_rcp_f32_e32 v244, v244
	v_rcp_f32_e32 v245, v245
	v_pk_mul_f32 v[238:239], v[238:239], v[242:243]
	v_pk_mul_f32 v[240:241], v[240:241], v[244:245]
	v_pk_mul_f32 v[80:81], v[80:81], v[238:239]
	v_pk_mul_f32 v[82:83], v[82:83], v[240:241]
	ds_read_u16_d16_hi v214, v2 offset:50720
	ds_read_u16_d16_hi v215, v2 offset:51248
	ds_read_u16_d16_hi v216, v2 offset:51776
	ds_read_u16_d16_hi v217, v2 offset:52304
	ds_read_u16_d16_hi v218, v2 offset:52832
	ds_read_u16_d16_hi v219, v2 offset:53360
	s_waitcnt lgkmcnt(6)
; DI float bf2f(u16 h) { return __uint_as_float(((unsigned)h) << 16); }
; DI float gelu_tanh(float x) { float u = 0.7978845608028654f * (x + 0.044715f * x * x * x); return x * sigmoidf_(2.f * u); }
; DI void ffup_tile(const Params& p, int l, int mt, int nt, char* smem) {
;     ...
; #pragma unroll
;       for (int m = 0; m < 8; ++m) {
;         if ((m & 1) == 0) asm volatile("" ::: "memory");
;         const int t = (row0 + wr * 128 + m * 16 + fq * 4) & 8191;
;         float g[6];
; #pragma unroll
;         for (int d = 0; d < 6; ++d) { const float gv = bf2f(img[(m * 16 + d) * IMG_LD + n * 16]); g[d] = (d >= 2 || t - 2 + d >= 0) ? gv : 0.f; }
; #pragma unroll
;         for (int j = 0; j < 4; ++j) acc[m][n][j] *= gelu_tanh(cb + w0 * g[j] + w1 * g[j + 1] + w2 * g[j + 2]);
;       }
	v_mov_b32_e32 v232, v227
	v_mov_b32_e32 v233, v228
	v_mov_b32_e32 v234, v229
	v_mov_b32_e32 v235, v230
	v_mov_b32_e32 v236, v231
	v_pk_fma_f32 v[238:239], v[162:163], v[226:227], v[168:169]
	v_pk_fma_f32 v[240:241], v[162:163], v[228:229], v[168:169]
	v_pk_fma_f32 v[238:239], v[164:165], v[232:233], v[238:239]
	v_pk_fma_f32 v[240:241], v[164:165], v[234:235], v[240:241]
	v_pk_fma_f32 v[238:239], v[166:167], v[228:229], v[238:239]
	v_pk_fma_f32 v[240:241], v[166:167], v[230:231], v[240:241]
	v_pk_mul_f32 v[242:243], v[176:177], v[238:239]
	v_pk_mul_f32 v[244:245], v[176:177], v[240:241]
	v_pk_mul_f32 v[242:243], v[238:239], v[242:243]
	v_pk_mul_f32 v[244:245], v[240:241], v[244:245]
	v_pk_fma_f32 v[242:243], v[238:239], v[242:243], v[238:239]
	v_pk_fma_f32 v[244:245], v[240:241], v[244:245], v[240:241]
	v_pk_mul_f32 v[242:243], v[178:179], v[242:243]
	v_pk_mul_f32 v[244:245], v[178:179], v[244:245]
	v_pk_add_f32 v[242:243], v[242:243], v[242:243]
	v_pk_add_f32 v[244:245], v[244:245], v[244:245]
	v_pk_mul_f32 v[242:243], v[180:181], v[242:243]
	v_pk_mul_f32 v[244:245], v[180:181], v[244:245]
	v_exp_f32_e32 v242, v242
	v_exp_f32_e32 v243, v243
	v_exp_f32_e32 v244, v244
	v_exp_f32_e32 v245, v245
	v_pk_add_f32 v[242:243], v[182:183], v[242:243]
	v_pk_add_f32 v[244:245], v[182:183], v[244:245]
	v_rcp_f32_e32 v242, v242
	v_rcp_f32_e32 v243, v243
	v_rcp_f32_e32 v244, v244
	v_rcp_f32_e32 v245, v245
	v_pk_mul_f32 v[238:239], v[238:239], v[242:243]
	v_pk_mul_f32 v[240:241], v[240:241], v[244:245]
	v_pk_mul_f32 v[76:77], v[76:77], v[238:239]
	v_pk_mul_f32 v[78:79], v[78:79], v[240:241]
	ds_read_u16_d16_hi v226, v2 offset:59168
	ds_read_u16_d16_hi v227, v2 offset:59696
	ds_read_u16_d16_hi v228, v2 offset:60224
	ds_read_u16_d16_hi v229, v2 offset:60752
	ds_read_u16_d16_hi v230, v2 offset:61280
	ds_read_u16_d16_hi v231, v2 offset:61808
	s_waitcnt lgkmcnt(6)
	v_mov_b32_e32 v220, v215
	v_mov_b32_e32 v221, v216
	v_mov_b32_e32 v222, v217
	v_mov_b32_e32 v223, v218
	v_mov_b32_e32 v224, v219
	v_pk_fma_f32 v[238:239], v[162:163], v[214:215], v[168:169]
	v_pk_fma_f32 v[240:241], v[162:163], v[216:217], v[168:169]
	v_pk_fma_f32 v[238:239], v[164:165], v[220:221], v[238:239]
	v_pk_fma_f32 v[240:241], v[164:165], v[222:223], v[240:241]
	v_pk_fma_f32 v[238:239], v[166:167], v[216:217], v[238:239]
	v_pk_fma_f32 v[240:241], v[166:167], v[218:219], v[240:241]
	v_pk_mul_f32 v[242:243], v[176:177], v[238:239]
	v_pk_mul_f32 v[244:245], v[176:177], v[240:241]
	v_pk_mul_f32 v[242:243], v[238:239], v[242:243]
	v_pk_mul_f32 v[244:245], v[240:241], v[244:245]
	v_pk_fma_f32 v[242:243], v[238:239], v[242:243], v[238:239]
	v_pk_fma_f32 v[244:245], v[240:241], v[244:245], v[240:241]
	v_pk_mul_f32 v[242:243], v[178:179], v[242:243]
	v_pk_mul_f32 v[244:245], v[178:179], v[244:245]
	v_pk_add_f32 v[242:243], v[242:243], v[242:243]
	v_pk_add_f32 v[244:245], v[244:245], v[244:245]
	v_pk_mul_f32 v[242:243], v[180:181], v[242:243]
	v_pk_mul_f32 v[244:245], v[180:181], v[244:245]
	v_exp_f32_e32 v242, v242
	v_exp_f32_e32 v243, v243
	v_exp_f32_e32 v244, v244
	v_exp_f32_e32 v245, v245
	v_pk_add_f32 v[242:243], v[182:183], v[242:243]
	v_pk_add_f32 v[244:245], v[182:183], v[244:245]
	v_rcp_f32_e32 v242, v242
	v_rcp_f32_e32 v243, v243
	v_rcp_f32_e32 v244, v244
	v_rcp_f32_e32 v245, v245
	v_pk_mul_f32 v[238:239], v[238:239], v[242:243]
	v_pk_mul_f32 v[240:241], v[240:241], v[244:245]
	v_pk_mul_f32 v[72:73], v[72:73], v[238:239]
	v_pk_mul_f32 v[74:75], v[74:75], v[240:241]
	ds_read_u16_d16_hi v214, v2 offset:64
	ds_read_u16_d16_hi v215, v2 offset:592
	ds_read_u16_d16_hi v216, v2 offset:1120
	ds_read_u16_d16_hi v217, v2 offset:1648
	ds_read_u16_d16_hi v218, v2 offset:2176
	ds_read_u16_d16_hi v219, v2 offset:2704
	s_waitcnt lgkmcnt(6)
	v_mov_b32_e32 v232, v227
	v_mov_b32_e32 v233, v228
	v_mov_b32_e32 v234, v229
	v_mov_b32_e32 v235, v230
	v_mov_b32_e32 v236, v231
	v_pk_fma_f32 v[238:239], v[162:163], v[226:227], v[168:169]
	v_pk_fma_f32 v[240:241], v[162:163], v[228:229], v[168:169]
	v_pk_fma_f32 v[238:239], v[164:165], v[232:233], v[238:239]
	v_pk_fma_f32 v[240:241], v[164:165], v[234:235], v[240:241]
	v_pk_fma_f32 v[238:239], v[166:167], v[228:229], v[238:239]
	v_pk_fma_f32 v[240:241], v[166:167], v[230:231], v[240:241]
	v_pk_mul_f32 v[242:243], v[176:177], v[238:239]
	v_pk_mul_f32 v[244:245], v[176:177], v[240:241]
	v_pk_mul_f32 v[242:243], v[238:239], v[242:243]
	v_pk_mul_f32 v[244:245], v[240:241], v[244:245]
	v_pk_fma_f32 v[242:243], v[238:239], v[242:243], v[238:239]
	v_pk_fma_f32 v[244:245], v[240:241], v[244:245], v[240:241]
	v_pk_mul_f32 v[242:243], v[178:179], v[242:243]
	v_pk_mul_f32 v[244:245], v[178:179], v[244:245]
	v_pk_add_f32 v[242:243], v[242:243], v[242:243]
	v_pk_add_f32 v[244:245], v[244:245], v[244:245]
	v_pk_mul_f32 v[242:243], v[180:181], v[242:243]
	v_pk_mul_f32 v[244:245], v[180:181], v[244:245]
	v_exp_f32_e32 v242, v242
	v_exp_f32_e32 v243, v243
	v_exp_f32_e32 v244, v244
	v_exp_f32_e32 v245, v245
	v_pk_add_f32 v[242:243], v[182:183], v[242:243]
	v_pk_add_f32 v[244:245], v[182:183], v[244:245]
	v_rcp_f32_e32 v242, v242
	v_rcp_f32_e32 v243, v243
	v_rcp_f32_e32 v244, v244
	v_rcp_f32_e32 v245, v245
	v_pk_mul_f32 v[238:239], v[238:239], v[242:243]
	v_pk_mul_f32 v[240:241], v[240:241], v[244:245]
	v_pk_mul_f32 v[68:69], v[68:69], v[238:239]
	v_pk_mul_f32 v[70:71], v[70:71], v[240:241]
	ds_read_u16_d16_hi v226, v2 offset:8512
	ds_read_u16_d16_hi v227, v2 offset:9040
	ds_read_u16_d16_hi v228, v2 offset:9568
	ds_read_u16_d16_hi v229, v2 offset:10096
	ds_read_u16_d16_hi v230, v2 offset:10624
	ds_read_u16_d16_hi v231, v2 offset:11152
	s_waitcnt lgkmcnt(6)
	s_waitcnt vmcnt(4)
; DI float bf2f(u16 h) { return __uint_as_float(((unsigned)h) << 16); }
; DI float gelu_tanh(float x) { float u = 0.7978845608028654f * (x + 0.044715f * x * x * x); return x * sigmoidf_(2.f * u); }
; DI void ffup_tile(const Params& p, int l, int mt, int nt, char* smem) {
;     ...
;     for (int n = 0; n < 4; ++n) {
;       const int col = col0 + wc * 64 + n * 16 + fr;
;       const float* cw = p.in[30] + (size_t)l * 3 * DFF + col;
;       const float w0 = cw[0], w1 = cw[DFF], w2 = cw[2 * DFF], cb = p.in[31][(size_t)l * DFF + col];
; #pragma unroll
;       for (int m = 0; m < 8; ++m) {
;         if ((m & 1) == 0) asm volatile("" ::: "memory");
;         const int t = (row0 + wr * 128 + m * 16 + fq * 4) & 8191;
;         float g[6];
; #pragma unroll
;         for (int d = 0; d < 6; ++d) { const float gv = bf2f(img[(m * 16 + d) * IMG_LD + n * 16]); g[d] = (d >= 2 || t - 2 + d >= 0) ? gv : 0.f; }
; #pragma unroll
;         for (int j = 0; j < 4; ++j) acc[m][n][j] *= gelu_tanh(cb + w0 * g[j] + w1 * g[j + 1] + w2 * g[j + 2]);
;       }
	v_mov_b32_e32 v162, v154
	v_mov_b32_e32 v163, v154
	v_mov_b32_e32 v164, v155
	v_mov_b32_e32 v165, v155
	v_mov_b32_e32 v166, v156
	v_mov_b32_e32 v167, v156
	v_mov_b32_e32 v168, v157
	v_mov_b32_e32 v169, v157
	v_cndmask_b32_e64 v214, v214, 0, vcc
	v_cndmask_b32_e64 v215, v215, 0, vcc
	v_mov_b32_e32 v220, v215
	v_mov_b32_e32 v221, v216
	v_mov_b32_e32 v222, v217
	v_mov_b32_e32 v223, v218
	v_mov_b32_e32 v224, v219
	v_pk_fma_f32 v[238:239], v[162:163], v[214:215], v[168:169]
	v_pk_fma_f32 v[240:241], v[162:163], v[216:217], v[168:169]
	v_pk_fma_f32 v[238:239], v[164:165], v[220:221], v[238:239]
	v_pk_fma_f32 v[240:241], v[164:165], v[222:223], v[240:241]
	v_pk_fma_f32 v[238:239], v[166:167], v[216:217], v[238:239]
	v_pk_fma_f32 v[240:241], v[166:167], v[218:219], v[240:241]
	v_pk_mul_f32 v[242:243], v[176:177], v[238:239]
	v_pk_mul_f32 v[244:245], v[176:177], v[240:241]
	v_pk_mul_f32 v[242:243], v[238:239], v[242:243]
	v_pk_mul_f32 v[244:245], v[240:241], v[244:245]
	v_pk_fma_f32 v[242:243], v[238:239], v[242:243], v[238:239]
	v_pk_fma_f32 v[244:245], v[240:241], v[244:245], v[240:241]
	v_pk_mul_f32 v[242:243], v[178:179], v[242:243]
	v_pk_mul_f32 v[244:245], v[178:179], v[244:245]
	v_pk_add_f32 v[242:243], v[242:243], v[242:243]
	v_pk_add_f32 v[244:245], v[244:245], v[244:245]
	v_pk_mul_f32 v[242:243], v[180:181], v[242:243]
	v_pk_mul_f32 v[244:245], v[180:181], v[244:245]
	v_exp_f32_e32 v242, v242
	v_exp_f32_e32 v243, v243
	v_exp_f32_e32 v244, v244
	v_exp_f32_e32 v245, v245
	v_pk_add_f32 v[242:243], v[182:183], v[242:243]
	v_pk_add_f32 v[244:245], v[182:183], v[244:245]
	v_rcp_f32_e32 v242, v242
	v_rcp_f32_e32 v243, v243
	v_rcp_f32_e32 v244, v244
	v_rcp_f32_e32 v245, v245
	v_pk_mul_f32 v[238:239], v[238:239], v[242:243]
	v_pk_mul_f32 v[240:241], v[240:241], v[244:245]
	v_pk_mul_f32 v[64:65], v[64:65], v[238:239]
	v_pk_mul_f32 v[66:67], v[66:67], v[240:241]
	ds_read_u16_d16_hi v214, v2 offset:16960
	ds_read_u16_d16_hi v215, v2 offset:17488
	ds_read_u16_d16_hi v216, v2 offset:18016
	ds_read_u16_d16_hi v217, v2 offset:18544
	ds_read_u16_d16_hi v218, v2 offset:19072
	ds_read_u16_d16_hi v219, v2 offset:19600
	s_waitcnt lgkmcnt(6)
	v_mov_b32_e32 v232, v227
	v_mov_b32_e32 v233, v228
	v_mov_b32_e32 v234, v229
	v_mov_b32_e32 v235, v230
	v_mov_b32_e32 v236, v231
	v_pk_fma_f32 v[238:239], v[162:163], v[226:227], v[168:169]
	v_pk_fma_f32 v[240:241], v[162:163], v[228:229], v[168:169]
	v_pk_fma_f32 v[238:239], v[164:165], v[232:233], v[238:239]
	v_pk_fma_f32 v[240:241], v[164:165], v[234:235], v[240:241]
	v_pk_fma_f32 v[238:239], v[166:167], v[228:229], v[238:239]
	v_pk_fma_f32 v[240:241], v[166:167], v[230:231], v[240:241]
	v_pk_mul_f32 v[242:243], v[176:177], v[238:239]
	v_pk_mul_f32 v[244:245], v[176:177], v[240:241]
	v_pk_mul_f32 v[242:243], v[238:239], v[242:243]
	v_pk_mul_f32 v[244:245], v[240:241], v[244:245]
	v_pk_fma_f32 v[242:243], v[238:239], v[242:243], v[238:239]
	v_pk_fma_f32 v[244:245], v[240:241], v[244:245], v[240:241]
	v_pk_mul_f32 v[242:243], v[178:179], v[242:243]
	v_pk_mul_f32 v[244:245], v[178:179], v[244:245]
	v_pk_add_f32 v[242:243], v[242:243], v[242:243]
	v_pk_add_f32 v[244:245], v[244:245], v[244:245]
	v_pk_mul_f32 v[242:243], v[180:181], v[242:243]
	v_pk_mul_f32 v[244:245], v[180:181], v[244:245]
	v_exp_f32_e32 v242, v242
	v_exp_f32_e32 v243, v243
	v_exp_f32_e32 v244, v244
	v_exp_f32_e32 v245, v245
	v_pk_add_f32 v[242:243], v[182:183], v[242:243]
	v_pk_add_f32 v[244:245], v[182:183], v[244:245]
	v_rcp_f32_e32 v242, v242
	v_rcp_f32_e32 v243, v243
	v_rcp_f32_e32 v244, v244
	v_rcp_f32_e32 v245, v245
	v_pk_mul_f32 v[238:239], v[238:239], v[242:243]
	v_pk_mul_f32 v[240:241], v[240:241], v[244:245]
	v_pk_mul_f32 v[60:61], v[60:61], v[238:239]
	v_pk_mul_f32 v[62:63], v[62:63], v[240:241]
	ds_read_u16_d16_hi v226, v2 offset:25408
	ds_read_u16_d16_hi v227, v2 offset:25936
	ds_read_u16_d16_hi v228, v2 offset:26464
	ds_read_u16_d16_hi v229, v2 offset:26992
	ds_read_u16_d16_hi v230, v2 offset:27520
	ds_read_u16_d16_hi v231, v2 offset:28048
	s_waitcnt lgkmcnt(6)
	v_mov_b32_e32 v220, v215
	v_mov_b32_e32 v221, v216
	v_mov_b32_e32 v222, v217
	v_mov_b32_e32 v223, v218
	v_mov_b32_e32 v224, v219
	v_pk_fma_f32 v[238:239], v[162:163], v[214:215], v[168:169]
	v_pk_fma_f32 v[240:241], v[162:163], v[216:217], v[168:169]
	v_pk_fma_f32 v[238:239], v[164:165], v[220:221], v[238:239]
	v_pk_fma_f32 v[240:241], v[164:165], v[222:223], v[240:241]
	v_pk_fma_f32 v[238:239], v[166:167], v[216:217], v[238:239]
	v_pk_fma_f32 v[240:241], v[166:167], v[218:219], v[240:241]
	v_pk_mul_f32 v[242:243], v[176:177], v[238:239]
	v_pk_mul_f32 v[244:245], v[176:177], v[240:241]
	v_pk_mul_f32 v[242:243], v[238:239], v[242:243]
	v_pk_mul_f32 v[244:245], v[240:241], v[244:245]
	v_pk_fma_f32 v[242:243], v[238:239], v[242:243], v[238:239]
	v_pk_fma_f32 v[244:245], v[240:241], v[244:245], v[240:241]
	v_pk_mul_f32 v[242:243], v[178:179], v[242:243]
	v_pk_mul_f32 v[244:245], v[178:179], v[244:245]
	v_pk_add_f32 v[242:243], v[242:243], v[242:243]
	v_pk_add_f32 v[244:245], v[244:245], v[244:245]
	v_pk_mul_f32 v[242:243], v[180:181], v[242:243]
	v_pk_mul_f32 v[244:245], v[180:181], v[244:245]
	v_exp_f32_e32 v242, v242
	v_exp_f32_e32 v243, v243
	v_exp_f32_e32 v244, v244
	v_exp_f32_e32 v245, v245
	v_pk_add_f32 v[242:243], v[182:183], v[242:243]
	v_pk_add_f32 v[244:245], v[182:183], v[244:245]
	v_rcp_f32_e32 v242, v242
	v_rcp_f32_e32 v243, v243
	v_rcp_f32_e32 v244, v244
	v_rcp_f32_e32 v245, v245
	v_pk_mul_f32 v[238:239], v[238:239], v[242:243]
	v_pk_mul_f32 v[240:241], v[240:241], v[244:245]
	v_pk_mul_f32 v[56:57], v[56:57], v[238:239]
	v_pk_mul_f32 v[58:59], v[58:59], v[240:241]
	ds_read_u16_d16_hi v214, v2 offset:33856
	ds_read_u16_d16_hi v215, v2 offset:34384
	ds_read_u16_d16_hi v216, v2 offset:34912
	ds_read_u16_d16_hi v217, v2 offset:35440
	ds_read_u16_d16_hi v218, v2 offset:35968
	ds_read_u16_d16_hi v219, v2 offset:36496
	s_waitcnt lgkmcnt(6)
; DI float bf2f(u16 h) { return __uint_as_float(((unsigned)h) << 16); }
; DI float gelu_tanh(float x) { float u = 0.7978845608028654f * (x + 0.044715f * x * x * x); return x * sigmoidf_(2.f * u); }
; DI void ffup_tile(const Params& p, int l, int mt, int nt, char* smem) {
;     ...
; #pragma unroll
;       for (int m = 0; m < 8; ++m) {
;         if ((m & 1) == 0) asm volatile("" ::: "memory");
;         const int t = (row0 + wr * 128 + m * 16 + fq * 4) & 8191;
;         float g[6];
; #pragma unroll
;         for (int d = 0; d < 6; ++d) { const float gv = bf2f(img[(m * 16 + d) * IMG_LD + n * 16]); g[d] = (d >= 2 || t - 2 + d >= 0) ? gv : 0.f; }
; #pragma unroll
;         for (int j = 0; j < 4; ++j) acc[m][n][j] *= gelu_tanh(cb + w0 * g[j] + w1 * g[j + 1] + w2 * g[j + 2]);
;       }
	v_mov_b32_e32 v232, v227
	v_mov_b32_e32 v233, v228
	v_mov_b32_e32 v234, v229
	v_mov_b32_e32 v235, v230
	v_mov_b32_e32 v236, v231
	v_pk_fma_f32 v[238:239], v[162:163], v[226:227], v[168:169]
	v_pk_fma_f32 v[240:241], v[162:163], v[228:229], v[168:169]
	v_pk_fma_f32 v[238:239], v[164:165], v[232:233], v[238:239]
	v_pk_fma_f32 v[240:241], v[164:165], v[234:235], v[240:241]
	v_pk_fma_f32 v[238:239], v[166:167], v[228:229], v[238:239]
	v_pk_fma_f32 v[240:241], v[166:167], v[230:231], v[240:241]
	v_pk_mul_f32 v[242:243], v[176:177], v[238:239]
	v_pk_mul_f32 v[244:245], v[176:177], v[240:241]
	v_pk_mul_f32 v[242:243], v[238:239], v[242:243]
	v_pk_mul_f32 v[244:245], v[240:241], v[244:245]
	v_pk_fma_f32 v[242:243], v[238:239], v[242:243], v[238:239]
	v_pk_fma_f32 v[244:245], v[240:241], v[244:245], v[240:241]
	v_pk_mul_f32 v[242:243], v[178:179], v[242:243]
	v_pk_mul_f32 v[244:245], v[178:179], v[244:245]
	v_pk_add_f32 v[242:243], v[242:243], v[242:243]
	v_pk_add_f32 v[244:245], v[244:245], v[244:245]
	v_pk_mul_f32 v[242:243], v[180:181], v[242:243]
	v_pk_mul_f32 v[244:245], v[180:181], v[244:245]
	v_exp_f32_e32 v242, v242
	v_exp_f32_e32 v243, v243
	v_exp_f32_e32 v244, v244
	v_exp_f32_e32 v245, v245
	v_pk_add_f32 v[242:243], v[182:183], v[242:243]
	v_pk_add_f32 v[244:245], v[182:183], v[244:245]
	v_rcp_f32_e32 v242, v242
	v_rcp_f32_e32 v243, v243
	v_rcp_f32_e32 v244, v244
	v_rcp_f32_e32 v245, v245
	v_pk_mul_f32 v[238:239], v[238:239], v[242:243]
	v_pk_mul_f32 v[240:241], v[240:241], v[244:245]
	v_pk_mul_f32 v[52:53], v[52:53], v[238:239]
	v_pk_mul_f32 v[54:55], v[54:55], v[240:241]
	ds_read_u16_d16_hi v226, v2 offset:42304
	ds_read_u16_d16_hi v227, v2 offset:42832
	ds_read_u16_d16_hi v228, v2 offset:43360
	ds_read_u16_d16_hi v229, v2 offset:43888
	ds_read_u16_d16_hi v230, v2 offset:44416
	ds_read_u16_d16_hi v231, v2 offset:44944
	s_waitcnt lgkmcnt(6)
	v_mov_b32_e32 v220, v215
	v_mov_b32_e32 v221, v216
	v_mov_b32_e32 v222, v217
	v_mov_b32_e32 v223, v218
	v_mov_b32_e32 v224, v219
	v_pk_fma_f32 v[238:239], v[162:163], v[214:215], v[168:169]
	v_pk_fma_f32 v[240:241], v[162:163], v[216:217], v[168:169]
	v_pk_fma_f32 v[238:239], v[164:165], v[220:221], v[238:239]
	v_pk_fma_f32 v[240:241], v[164:165], v[222:223], v[240:241]
	v_pk_fma_f32 v[238:239], v[166:167], v[216:217], v[238:239]
	v_pk_fma_f32 v[240:241], v[166:167], v[218:219], v[240:241]
	v_pk_mul_f32 v[242:243], v[176:177], v[238:239]
	v_pk_mul_f32 v[244:245], v[176:177], v[240:241]
	v_pk_mul_f32 v[242:243], v[238:239], v[242:243]
	v_pk_mul_f32 v[244:245], v[240:241], v[244:245]
	v_pk_fma_f32 v[242:243], v[238:239], v[242:243], v[238:239]
	v_pk_fma_f32 v[244:245], v[240:241], v[244:245], v[240:241]
	v_pk_mul_f32 v[242:243], v[178:179], v[242:243]
	v_pk_mul_f32 v[244:245], v[178:179], v[244:245]
	v_pk_add_f32 v[242:243], v[242:243], v[242:243]
	v_pk_add_f32 v[244:245], v[244:245], v[244:245]
	v_pk_mul_f32 v[242:243], v[180:181], v[242:243]
	v_pk_mul_f32 v[244:245], v[180:181], v[244:245]
	v_exp_f32_e32 v242, v242
	v_exp_f32_e32 v243, v243
	v_exp_f32_e32 v244, v244
	v_exp_f32_e32 v245, v245
	v_pk_add_f32 v[242:243], v[182:183], v[242:243]
	v_pk_add_f32 v[244:245], v[182:183], v[244:245]
	v_rcp_f32_e32 v242, v242
	v_rcp_f32_e32 v243, v243
	v_rcp_f32_e32 v244, v244
	v_rcp_f32_e32 v245, v245
	v_pk_mul_f32 v[238:239], v[238:239], v[242:243]
	v_pk_mul_f32 v[240:241], v[240:241], v[244:245]
	v_pk_mul_f32 v[48:49], v[48:49], v[238:239]
	v_pk_mul_f32 v[50:51], v[50:51], v[240:241]
	ds_read_u16_d16_hi v214, v2 offset:50752
	ds_read_u16_d16_hi v215, v2 offset:51280
	ds_read_u16_d16_hi v216, v2 offset:51808
	ds_read_u16_d16_hi v217, v2 offset:52336
	ds_read_u16_d16_hi v218, v2 offset:52864
	ds_read_u16_d16_hi v219, v2 offset:53392
	s_waitcnt lgkmcnt(6)
	v_mov_b32_e32 v232, v227
	v_mov_b32_e32 v233, v228
	v_mov_b32_e32 v234, v229
	v_mov_b32_e32 v235, v230
	v_mov_b32_e32 v236, v231
	v_pk_fma_f32 v[238:239], v[162:163], v[226:227], v[168:169]
	v_pk_fma_f32 v[240:241], v[162:163], v[228:229], v[168:169]
	v_pk_fma_f32 v[238:239], v[164:165], v[232:233], v[238:239]
	v_pk_fma_f32 v[240:241], v[164:165], v[234:235], v[240:241]
	v_pk_fma_f32 v[238:239], v[166:167], v[228:229], v[238:239]
	v_pk_fma_f32 v[240:241], v[166:167], v[230:231], v[240:241]
	v_pk_mul_f32 v[242:243], v[176:177], v[238:239]
	v_pk_mul_f32 v[244:245], v[176:177], v[240:241]
	v_pk_mul_f32 v[242:243], v[238:239], v[242:243]
	v_pk_mul_f32 v[244:245], v[240:241], v[244:245]
	v_pk_fma_f32 v[242:243], v[238:239], v[242:243], v[238:239]
	v_pk_fma_f32 v[244:245], v[240:241], v[244:245], v[240:241]
	v_pk_mul_f32 v[242:243], v[178:179], v[242:243]
	v_pk_mul_f32 v[244:245], v[178:179], v[244:245]
	v_pk_add_f32 v[242:243], v[242:243], v[242:243]
	v_pk_add_f32 v[244:245], v[244:245], v[244:245]
	v_pk_mul_f32 v[242:243], v[180:181], v[242:243]
	v_pk_mul_f32 v[244:245], v[180:181], v[244:245]
	v_exp_f32_e32 v242, v242
	v_exp_f32_e32 v243, v243
	v_exp_f32_e32 v244, v244
	v_exp_f32_e32 v245, v245
	v_pk_add_f32 v[242:243], v[182:183], v[242:243]
	v_pk_add_f32 v[244:245], v[182:183], v[244:245]
	v_rcp_f32_e32 v242, v242
	v_rcp_f32_e32 v243, v243
	v_rcp_f32_e32 v244, v244
	v_rcp_f32_e32 v245, v245
	v_pk_mul_f32 v[238:239], v[238:239], v[242:243]
	v_pk_mul_f32 v[240:241], v[240:241], v[244:245]
	v_pk_mul_f32 v[44:45], v[44:45], v[238:239]
	v_pk_mul_f32 v[46:47], v[46:47], v[240:241]
	ds_read_u16_d16_hi v226, v2 offset:59200
	ds_read_u16_d16_hi v227, v2 offset:59728
	ds_read_u16_d16_hi v228, v2 offset:60256
	ds_read_u16_d16_hi v229, v2 offset:60784
	ds_read_u16_d16_hi v230, v2 offset:61312
	ds_read_u16_d16_hi v231, v2 offset:61840
	s_waitcnt lgkmcnt(6)
; DI float bf2f(u16 h) { return __uint_as_float(((unsigned)h) << 16); }
; DI float gelu_tanh(float x) { float u = 0.7978845608028654f * (x + 0.044715f * x * x * x); return x * sigmoidf_(2.f * u); }
; DI void ffup_tile(const Params& p, int l, int mt, int nt, char* smem) {
;     ...
;     for (int n = 0; n < 4; ++n) {
;       const int col = col0 + wc * 64 + n * 16 + fr;
;       const float* cw = p.in[30] + (size_t)l * 3 * DFF + col;
;       const float w0 = cw[0], w1 = cw[DFF], w2 = cw[2 * DFF], cb = p.in[31][(size_t)l * DFF + col];
; #pragma unroll
;       for (int m = 0; m < 8; ++m) {
;         if ((m & 1) == 0) asm volatile("" ::: "memory");
;         const int t = (row0 + wr * 128 + m * 16 + fq * 4) & 8191;
;         float g[6];
; #pragma unroll
;         for (int d = 0; d < 6; ++d) { const float gv = bf2f(img[(m * 16 + d) * IMG_LD + n * 16]); g[d] = (d >= 2 || t - 2 + d >= 0) ? gv : 0.f; }
; #pragma unroll
;         for (int j = 0; j < 4; ++j) acc[m][n][j] *= gelu_tanh(cb + w0 * g[j] + w1 * g[j + 1] + w2 * g[j + 2]);
;       }
	v_mov_b32_e32 v220, v215
	v_mov_b32_e32 v221, v216
	v_mov_b32_e32 v222, v217
	v_mov_b32_e32 v223, v218
	v_mov_b32_e32 v224, v219
	v_pk_fma_f32 v[238:239], v[162:163], v[214:215], v[168:169]
	v_pk_fma_f32 v[240:241], v[162:163], v[216:217], v[168:169]
	v_pk_fma_f32 v[238:239], v[164:165], v[220:221], v[238:239]
	v_pk_fma_f32 v[240:241], v[164:165], v[222:223], v[240:241]
	v_pk_fma_f32 v[238:239], v[166:167], v[216:217], v[238:239]
	v_pk_fma_f32 v[240:241], v[166:167], v[218:219], v[240:241]
	v_pk_mul_f32 v[242:243], v[176:177], v[238:239]
	v_pk_mul_f32 v[244:245], v[176:177], v[240:241]
	v_pk_mul_f32 v[242:243], v[238:239], v[242:243]
	v_pk_mul_f32 v[244:245], v[240:241], v[244:245]
	v_pk_fma_f32 v[242:243], v[238:239], v[242:243], v[238:239]
	v_pk_fma_f32 v[244:245], v[240:241], v[244:245], v[240:241]
	v_pk_mul_f32 v[242:243], v[178:179], v[242:243]
	v_pk_mul_f32 v[244:245], v[178:179], v[244:245]
	v_pk_add_f32 v[242:243], v[242:243], v[242:243]
	v_pk_add_f32 v[244:245], v[244:245], v[244:245]
	v_pk_mul_f32 v[242:243], v[180:181], v[242:243]
	v_pk_mul_f32 v[244:245], v[180:181], v[244:245]
	v_exp_f32_e32 v242, v242
	v_exp_f32_e32 v243, v243
	v_exp_f32_e32 v244, v244
	v_exp_f32_e32 v245, v245
	v_pk_add_f32 v[242:243], v[182:183], v[242:243]
	v_pk_add_f32 v[244:245], v[182:183], v[244:245]
	v_rcp_f32_e32 v242, v242
	v_rcp_f32_e32 v243, v243
	v_rcp_f32_e32 v244, v244
	v_rcp_f32_e32 v245, v245
	v_pk_mul_f32 v[238:239], v[238:239], v[242:243]
	v_pk_mul_f32 v[240:241], v[240:241], v[244:245]
	v_pk_mul_f32 v[40:41], v[40:41], v[238:239]
	v_pk_mul_f32 v[42:43], v[42:43], v[240:241]
	ds_read_u16_d16_hi v214, v2 offset:96
	ds_read_u16_d16_hi v215, v2 offset:624
	ds_read_u16_d16_hi v216, v2 offset:1152
	ds_read_u16_d16_hi v217, v2 offset:1680
	ds_read_u16_d16_hi v218, v2 offset:2208
	ds_read_u16_d16_hi v219, v2 offset:2736
	s_waitcnt lgkmcnt(6)
	v_mov_b32_e32 v232, v227
	v_mov_b32_e32 v233, v228
	v_mov_b32_e32 v234, v229
	v_mov_b32_e32 v235, v230
	v_mov_b32_e32 v236, v231
	v_pk_fma_f32 v[238:239], v[162:163], v[226:227], v[168:169]
	v_pk_fma_f32 v[240:241], v[162:163], v[228:229], v[168:169]
	v_pk_fma_f32 v[238:239], v[164:165], v[232:233], v[238:239]
	v_pk_fma_f32 v[240:241], v[164:165], v[234:235], v[240:241]
	v_pk_fma_f32 v[238:239], v[166:167], v[228:229], v[238:239]
	v_pk_fma_f32 v[240:241], v[166:167], v[230:231], v[240:241]
	v_pk_mul_f32 v[242:243], v[176:177], v[238:239]
	v_pk_mul_f32 v[244:245], v[176:177], v[240:241]
	v_pk_mul_f32 v[242:243], v[238:239], v[242:243]
	v_pk_mul_f32 v[244:245], v[240:241], v[244:245]
	v_pk_fma_f32 v[242:243], v[238:239], v[242:243], v[238:239]
	v_pk_fma_f32 v[244:245], v[240:241], v[244:245], v[240:241]
	v_pk_mul_f32 v[242:243], v[178:179], v[242:243]
	v_pk_mul_f32 v[244:245], v[178:179], v[244:245]
	v_pk_add_f32 v[242:243], v[242:243], v[242:243]
	v_pk_add_f32 v[244:245], v[244:245], v[244:245]
	v_pk_mul_f32 v[242:243], v[180:181], v[242:243]
	v_pk_mul_f32 v[244:245], v[180:181], v[244:245]
	v_exp_f32_e32 v242, v242
	v_exp_f32_e32 v243, v243
	v_exp_f32_e32 v244, v244
	v_exp_f32_e32 v245, v245
	v_pk_add_f32 v[242:243], v[182:183], v[242:243]
	v_pk_add_f32 v[244:245], v[182:183], v[244:245]
	v_rcp_f32_e32 v242, v242
	v_rcp_f32_e32 v243, v243
	v_rcp_f32_e32 v244, v244
	v_rcp_f32_e32 v245, v245
	v_pk_mul_f32 v[238:239], v[238:239], v[242:243]
	v_pk_mul_f32 v[240:241], v[240:241], v[244:245]
	v_pk_mul_f32 v[36:37], v[36:37], v[238:239]
	v_pk_mul_f32 v[38:39], v[38:39], v[240:241]
	ds_read_u16_d16_hi v226, v2 offset:8544
	ds_read_u16_d16_hi v227, v2 offset:9072
	ds_read_u16_d16_hi v228, v2 offset:9600
	ds_read_u16_d16_hi v229, v2 offset:10128
	ds_read_u16_d16_hi v230, v2 offset:10656
	ds_read_u16_d16_hi v231, v2 offset:11184
	s_waitcnt lgkmcnt(6)
	s_waitcnt vmcnt(0)
	v_mov_b32_e32 v162, v158
	v_mov_b32_e32 v163, v158
	v_mov_b32_e32 v164, v159
	v_mov_b32_e32 v165, v159
	v_mov_b32_e32 v166, v160
	v_mov_b32_e32 v167, v160
	v_mov_b32_e32 v168, v161
	v_mov_b32_e32 v169, v161
	v_cndmask_b32_e64 v214, v214, 0, vcc
	v_cndmask_b32_e64 v215, v215, 0, vcc
	v_mov_b32_e32 v220, v215
	v_mov_b32_e32 v221, v216
	v_mov_b32_e32 v222, v217
	v_mov_b32_e32 v223, v218
	v_mov_b32_e32 v224, v219
	v_pk_fma_f32 v[238:239], v[162:163], v[214:215], v[168:169]
	v_pk_fma_f32 v[240:241], v[162:163], v[216:217], v[168:169]
	v_pk_fma_f32 v[238:239], v[164:165], v[220:221], v[238:239]
	v_pk_fma_f32 v[240:241], v[164:165], v[222:223], v[240:241]
	v_pk_fma_f32 v[238:239], v[166:167], v[216:217], v[238:239]
	v_pk_fma_f32 v[240:241], v[166:167], v[218:219], v[240:241]
	v_pk_mul_f32 v[242:243], v[176:177], v[238:239]
	v_pk_mul_f32 v[244:245], v[176:177], v[240:241]
	v_pk_mul_f32 v[242:243], v[238:239], v[242:243]
	v_pk_mul_f32 v[244:245], v[240:241], v[244:245]
	v_pk_fma_f32 v[242:243], v[238:239], v[242:243], v[238:239]
	v_pk_fma_f32 v[244:245], v[240:241], v[244:245], v[240:241]
	v_pk_mul_f32 v[242:243], v[178:179], v[242:243]
	v_pk_mul_f32 v[244:245], v[178:179], v[244:245]
	v_pk_add_f32 v[242:243], v[242:243], v[242:243]
	v_pk_add_f32 v[244:245], v[244:245], v[244:245]
	v_pk_mul_f32 v[242:243], v[180:181], v[242:243]
	v_pk_mul_f32 v[244:245], v[180:181], v[244:245]
	v_exp_f32_e32 v242, v242
	v_exp_f32_e32 v243, v243
	v_exp_f32_e32 v244, v244
	v_exp_f32_e32 v245, v245
	v_pk_add_f32 v[242:243], v[182:183], v[242:243]
	v_pk_add_f32 v[244:245], v[182:183], v[244:245]
	v_rcp_f32_e32 v242, v242
	v_rcp_f32_e32 v243, v243
	v_rcp_f32_e32 v244, v244
	v_rcp_f32_e32 v245, v245
	v_pk_mul_f32 v[238:239], v[238:239], v[242:243]
	v_pk_mul_f32 v[240:241], v[240:241], v[244:245]
	v_pk_mul_f32 v[32:33], v[32:33], v[238:239]
	v_pk_mul_f32 v[34:35], v[34:35], v[240:241]
	ds_read_u16_d16_hi v214, v2 offset:16992
	ds_read_u16_d16_hi v215, v2 offset:17520
	ds_read_u16_d16_hi v216, v2 offset:18048
	ds_read_u16_d16_hi v217, v2 offset:18576
	ds_read_u16_d16_hi v218, v2 offset:19104
	ds_read_u16_d16_hi v219, v2 offset:19632
	s_waitcnt lgkmcnt(6)
; DI float bf2f(u16 h) { return __uint_as_float(((unsigned)h) << 16); }
; DI float gelu_tanh(float x) { float u = 0.7978845608028654f * (x + 0.044715f * x * x * x); return x * sigmoidf_(2.f * u); }
; DI void ffup_tile(const Params& p, int l, int mt, int nt, char* smem) {
;     ...
; #pragma unroll
;       for (int m = 0; m < 8; ++m) {
;         if ((m & 1) == 0) asm volatile("" ::: "memory");
;         const int t = (row0 + wr * 128 + m * 16 + fq * 4) & 8191;
;         float g[6];
; #pragma unroll
;         for (int d = 0; d < 6; ++d) { const float gv = bf2f(img[(m * 16 + d) * IMG_LD + n * 16]); g[d] = (d >= 2 || t - 2 + d >= 0) ? gv : 0.f; }
; #pragma unroll
;         for (int j = 0; j < 4; ++j) acc[m][n][j] *= gelu_tanh(cb + w0 * g[j] + w1 * g[j + 1] + w2 * g[j + 2]);
;       }
	v_mov_b32_e32 v232, v227
	v_mov_b32_e32 v233, v228
	v_mov_b32_e32 v234, v229
	v_mov_b32_e32 v235, v230
	v_mov_b32_e32 v236, v231
	v_pk_fma_f32 v[238:239], v[162:163], v[226:227], v[168:169]
	v_pk_fma_f32 v[240:241], v[162:163], v[228:229], v[168:169]
	v_pk_fma_f32 v[238:239], v[164:165], v[232:233], v[238:239]
	v_pk_fma_f32 v[240:241], v[164:165], v[234:235], v[240:241]
	v_pk_fma_f32 v[238:239], v[166:167], v[228:229], v[238:239]
	v_pk_fma_f32 v[240:241], v[166:167], v[230:231], v[240:241]
	v_pk_mul_f32 v[242:243], v[176:177], v[238:239]
	v_pk_mul_f32 v[244:245], v[176:177], v[240:241]
	v_pk_mul_f32 v[242:243], v[238:239], v[242:243]
	v_pk_mul_f32 v[244:245], v[240:241], v[244:245]
	v_pk_fma_f32 v[242:243], v[238:239], v[242:243], v[238:239]
	v_pk_fma_f32 v[244:245], v[240:241], v[244:245], v[240:241]
	v_pk_mul_f32 v[242:243], v[178:179], v[242:243]
	v_pk_mul_f32 v[244:245], v[178:179], v[244:245]
	v_pk_add_f32 v[242:243], v[242:243], v[242:243]
	v_pk_add_f32 v[244:245], v[244:245], v[244:245]
	v_pk_mul_f32 v[242:243], v[180:181], v[242:243]
	v_pk_mul_f32 v[244:245], v[180:181], v[244:245]
	v_exp_f32_e32 v242, v242
	v_exp_f32_e32 v243, v243
	v_exp_f32_e32 v244, v244
	v_exp_f32_e32 v245, v245
	v_pk_add_f32 v[242:243], v[182:183], v[242:243]
	v_pk_add_f32 v[244:245], v[182:183], v[244:245]
	v_rcp_f32_e32 v242, v242
	v_rcp_f32_e32 v243, v243
	v_rcp_f32_e32 v244, v244
	v_rcp_f32_e32 v245, v245
	v_pk_mul_f32 v[238:239], v[238:239], v[242:243]
	v_pk_mul_f32 v[240:241], v[240:241], v[244:245]
	v_pk_mul_f32 v[28:29], v[28:29], v[238:239]
	v_pk_mul_f32 v[30:31], v[30:31], v[240:241]
	ds_read_u16_d16_hi v226, v2 offset:25440
	ds_read_u16_d16_hi v227, v2 offset:25968
	ds_read_u16_d16_hi v228, v2 offset:26496
	ds_read_u16_d16_hi v229, v2 offset:27024
	ds_read_u16_d16_hi v230, v2 offset:27552
	ds_read_u16_d16_hi v231, v2 offset:28080
	s_waitcnt lgkmcnt(6)
	v_mov_b32_e32 v220, v215
	v_mov_b32_e32 v221, v216
	v_mov_b32_e32 v222, v217
	v_mov_b32_e32 v223, v218
	v_mov_b32_e32 v224, v219
	v_pk_fma_f32 v[238:239], v[162:163], v[214:215], v[168:169]
	v_pk_fma_f32 v[240:241], v[162:163], v[216:217], v[168:169]
	v_pk_fma_f32 v[238:239], v[164:165], v[220:221], v[238:239]
	v_pk_fma_f32 v[240:241], v[164:165], v[222:223], v[240:241]
	v_pk_fma_f32 v[238:239], v[166:167], v[216:217], v[238:239]
	v_pk_fma_f32 v[240:241], v[166:167], v[218:219], v[240:241]
	v_pk_mul_f32 v[242:243], v[176:177], v[238:239]
	v_pk_mul_f32 v[244:245], v[176:177], v[240:241]
	v_pk_mul_f32 v[242:243], v[238:239], v[242:243]
	v_pk_mul_f32 v[244:245], v[240:241], v[244:245]
	v_pk_fma_f32 v[242:243], v[238:239], v[242:243], v[238:239]
	v_pk_fma_f32 v[244:245], v[240:241], v[244:245], v[240:241]
	v_pk_mul_f32 v[242:243], v[178:179], v[242:243]
	v_pk_mul_f32 v[244:245], v[178:179], v[244:245]
	v_pk_add_f32 v[242:243], v[242:243], v[242:243]
	v_pk_add_f32 v[244:245], v[244:245], v[244:245]
	v_pk_mul_f32 v[242:243], v[180:181], v[242:243]
	v_pk_mul_f32 v[244:245], v[180:181], v[244:245]
	v_exp_f32_e32 v242, v242
	v_exp_f32_e32 v243, v243
	v_exp_f32_e32 v244, v244
	v_exp_f32_e32 v245, v245
	v_pk_add_f32 v[242:243], v[182:183], v[242:243]
	v_pk_add_f32 v[244:245], v[182:183], v[244:245]
	v_rcp_f32_e32 v242, v242
	v_rcp_f32_e32 v243, v243
	v_rcp_f32_e32 v244, v244
	v_rcp_f32_e32 v245, v245
	v_pk_mul_f32 v[238:239], v[238:239], v[242:243]
	v_pk_mul_f32 v[240:241], v[240:241], v[244:245]
	v_pk_mul_f32 v[24:25], v[24:25], v[238:239]
	v_pk_mul_f32 v[26:27], v[26:27], v[240:241]
	ds_read_u16_d16_hi v214, v2 offset:33888
	ds_read_u16_d16_hi v215, v2 offset:34416
	ds_read_u16_d16_hi v216, v2 offset:34944
	ds_read_u16_d16_hi v217, v2 offset:35472
	ds_read_u16_d16_hi v218, v2 offset:36000
	ds_read_u16_d16_hi v219, v2 offset:36528
	s_waitcnt lgkmcnt(6)
	v_mov_b32_e32 v232, v227
	v_mov_b32_e32 v233, v228
	v_mov_b32_e32 v234, v229
	v_mov_b32_e32 v235, v230
	v_mov_b32_e32 v236, v231
	v_pk_fma_f32 v[238:239], v[162:163], v[226:227], v[168:169]
	v_pk_fma_f32 v[240:241], v[162:163], v[228:229], v[168:169]
	v_pk_fma_f32 v[238:239], v[164:165], v[232:233], v[238:239]
	v_pk_fma_f32 v[240:241], v[164:165], v[234:235], v[240:241]
	v_pk_fma_f32 v[238:239], v[166:167], v[228:229], v[238:239]
	v_pk_fma_f32 v[240:241], v[166:167], v[230:231], v[240:241]
	v_pk_mul_f32 v[242:243], v[176:177], v[238:239]
	v_pk_mul_f32 v[244:245], v[176:177], v[240:241]
	v_pk_mul_f32 v[242:243], v[238:239], v[242:243]
	v_pk_mul_f32 v[244:245], v[240:241], v[244:245]
	v_pk_fma_f32 v[242:243], v[238:239], v[242:243], v[238:239]
	v_pk_fma_f32 v[244:245], v[240:241], v[244:245], v[240:241]
	v_pk_mul_f32 v[242:243], v[178:179], v[242:243]
	v_pk_mul_f32 v[244:245], v[178:179], v[244:245]
	v_pk_add_f32 v[242:243], v[242:243], v[242:243]
	v_pk_add_f32 v[244:245], v[244:245], v[244:245]
	v_pk_mul_f32 v[242:243], v[180:181], v[242:243]
	v_pk_mul_f32 v[244:245], v[180:181], v[244:245]
	v_exp_f32_e32 v242, v242
	v_exp_f32_e32 v243, v243
	v_exp_f32_e32 v244, v244
	v_exp_f32_e32 v245, v245
	v_pk_add_f32 v[242:243], v[182:183], v[242:243]
	v_pk_add_f32 v[244:245], v[182:183], v[244:245]
	v_rcp_f32_e32 v242, v242
	v_rcp_f32_e32 v243, v243
	v_rcp_f32_e32 v244, v244
	v_rcp_f32_e32 v245, v245
	v_pk_mul_f32 v[238:239], v[238:239], v[242:243]
	v_pk_mul_f32 v[240:241], v[240:241], v[244:245]
	v_pk_mul_f32 v[20:21], v[20:21], v[238:239]
	v_pk_mul_f32 v[22:23], v[22:23], v[240:241]
	ds_read_u16_d16_hi v226, v2 offset:42336
	ds_read_u16_d16_hi v227, v2 offset:42864
	ds_read_u16_d16_hi v228, v2 offset:43392
	ds_read_u16_d16_hi v229, v2 offset:43920
	ds_read_u16_d16_hi v230, v2 offset:44448
	ds_read_u16_d16_hi v231, v2 offset:44976
	s_waitcnt lgkmcnt(6)
; DI float bf2f(u16 h) { return __uint_as_float(((unsigned)h) << 16); }
; DI float gelu_tanh(float x) { float u = 0.7978845608028654f * (x + 0.044715f * x * x * x); return x * sigmoidf_(2.f * u); }
; DI void img_barrier() { asm volatile("s_waitcnt lgkmcnt(0)" ::: "memory"); __builtin_amdgcn_s_barrier(); }
; DI void ffup_tile(const Params& p, int l, int mt, int nt, char* smem) {
;     ...
; #pragma unroll
;       for (int m = 0; m < 8; ++m) {
;         if ((m & 1) == 0) asm volatile("" ::: "memory");
;         const int t = (row0 + wr * 128 + m * 16 + fq * 4) & 8191;
;         float g[6];
; #pragma unroll
;         for (int d = 0; d < 6; ++d) { const float gv = bf2f(img[(m * 16 + d) * IMG_LD + n * 16]); g[d] = (d >= 2 || t - 2 + d >= 0) ? gv : 0.f; }
; #pragma unroll
;         for (int j = 0; j < 4; ++j) acc[m][n][j] *= gelu_tanh(cb + w0 * g[j] + w1 * g[j + 1] + w2 * g[j + 2]);
;       }
;     }
;     img_barrier();
	v_mov_b32_e32 v220, v215
	v_mov_b32_e32 v221, v216
	v_mov_b32_e32 v222, v217
	v_mov_b32_e32 v223, v218
	v_mov_b32_e32 v224, v219
	v_pk_fma_f32 v[238:239], v[162:163], v[214:215], v[168:169]
	v_pk_fma_f32 v[240:241], v[162:163], v[216:217], v[168:169]
	v_pk_fma_f32 v[238:239], v[164:165], v[220:221], v[238:239]
	v_pk_fma_f32 v[240:241], v[164:165], v[222:223], v[240:241]
	v_pk_fma_f32 v[238:239], v[166:167], v[216:217], v[238:239]
	v_pk_fma_f32 v[240:241], v[166:167], v[218:219], v[240:241]
	v_pk_mul_f32 v[242:243], v[176:177], v[238:239]
	v_pk_mul_f32 v[244:245], v[176:177], v[240:241]
	v_pk_mul_f32 v[242:243], v[238:239], v[242:243]
	v_pk_mul_f32 v[244:245], v[240:241], v[244:245]
	v_pk_fma_f32 v[242:243], v[238:239], v[242:243], v[238:239]
	v_pk_fma_f32 v[244:245], v[240:241], v[244:245], v[240:241]
	v_pk_mul_f32 v[242:243], v[178:179], v[242:243]
	v_pk_mul_f32 v[244:245], v[178:179], v[244:245]
	v_pk_add_f32 v[242:243], v[242:243], v[242:243]
	v_pk_add_f32 v[244:245], v[244:245], v[244:245]
	v_pk_mul_f32 v[242:243], v[180:181], v[242:243]
	v_pk_mul_f32 v[244:245], v[180:181], v[244:245]
	v_exp_f32_e32 v242, v242
	v_exp_f32_e32 v243, v243
	v_exp_f32_e32 v244, v244
	v_exp_f32_e32 v245, v245
	v_pk_add_f32 v[242:243], v[182:183], v[242:243]
	v_pk_add_f32 v[244:245], v[182:183], v[244:245]
	v_rcp_f32_e32 v242, v242
	v_rcp_f32_e32 v243, v243
	v_rcp_f32_e32 v244, v244
	v_rcp_f32_e32 v245, v245
	v_pk_mul_f32 v[238:239], v[238:239], v[242:243]
	v_pk_mul_f32 v[240:241], v[240:241], v[244:245]
	v_pk_mul_f32 v[16:17], v[16:17], v[238:239]
	v_pk_mul_f32 v[18:19], v[18:19], v[240:241]
	ds_read_u16_d16_hi v214, v2 offset:50784
	ds_read_u16_d16_hi v215, v2 offset:51312
	ds_read_u16_d16_hi v216, v2 offset:51840
	ds_read_u16_d16_hi v217, v2 offset:52368
	ds_read_u16_d16_hi v218, v2 offset:52896
	ds_read_u16_d16_hi v219, v2 offset:53424
	s_waitcnt lgkmcnt(6)
	v_mov_b32_e32 v232, v227
	v_mov_b32_e32 v233, v228
	v_mov_b32_e32 v234, v229
	v_mov_b32_e32 v235, v230
	v_mov_b32_e32 v236, v231
	v_pk_fma_f32 v[238:239], v[162:163], v[226:227], v[168:169]
	v_pk_fma_f32 v[240:241], v[162:163], v[228:229], v[168:169]
	v_pk_fma_f32 v[238:239], v[164:165], v[232:233], v[238:239]
	v_pk_fma_f32 v[240:241], v[164:165], v[234:235], v[240:241]
	v_pk_fma_f32 v[238:239], v[166:167], v[228:229], v[238:239]
	v_pk_fma_f32 v[240:241], v[166:167], v[230:231], v[240:241]
	v_pk_mul_f32 v[242:243], v[176:177], v[238:239]
	v_pk_mul_f32 v[244:245], v[176:177], v[240:241]
	v_pk_mul_f32 v[242:243], v[238:239], v[242:243]
	v_pk_mul_f32 v[244:245], v[240:241], v[244:245]
	v_pk_fma_f32 v[242:243], v[238:239], v[242:243], v[238:239]
	v_pk_fma_f32 v[244:245], v[240:241], v[244:245], v[240:241]
	v_pk_mul_f32 v[242:243], v[178:179], v[242:243]
	v_pk_mul_f32 v[244:245], v[178:179], v[244:245]
	v_pk_add_f32 v[242:243], v[242:243], v[242:243]
	v_pk_add_f32 v[244:245], v[244:245], v[244:245]
	v_pk_mul_f32 v[242:243], v[180:181], v[242:243]
	v_pk_mul_f32 v[244:245], v[180:181], v[244:245]
	v_exp_f32_e32 v242, v242
	v_exp_f32_e32 v243, v243
	v_exp_f32_e32 v244, v244
	v_exp_f32_e32 v245, v245
	v_pk_add_f32 v[242:243], v[182:183], v[242:243]
	v_pk_add_f32 v[244:245], v[182:183], v[244:245]
	v_rcp_f32_e32 v242, v242
	v_rcp_f32_e32 v243, v243
	v_rcp_f32_e32 v244, v244
	v_rcp_f32_e32 v245, v245
	v_pk_mul_f32 v[238:239], v[238:239], v[242:243]
	v_pk_mul_f32 v[240:241], v[240:241], v[244:245]
	v_pk_mul_f32 v[12:13], v[12:13], v[238:239]
	v_pk_mul_f32 v[14:15], v[14:15], v[240:241]
	ds_read_u16_d16_hi v226, v2 offset:59232
	ds_read_u16_d16_hi v227, v2 offset:59760
	ds_read_u16_d16_hi v228, v2 offset:60288
	ds_read_u16_d16_hi v229, v2 offset:60816
	ds_read_u16_d16_hi v230, v2 offset:61344
	ds_read_u16_d16_hi v231, v2 offset:61872
	s_waitcnt lgkmcnt(6)
	v_mov_b32_e32 v220, v215
	v_mov_b32_e32 v221, v216
	v_mov_b32_e32 v222, v217
	v_mov_b32_e32 v223, v218
	v_mov_b32_e32 v224, v219
	v_pk_fma_f32 v[238:239], v[162:163], v[214:215], v[168:169]
	v_pk_fma_f32 v[240:241], v[162:163], v[216:217], v[168:169]
	v_pk_fma_f32 v[238:239], v[164:165], v[220:221], v[238:239]
	v_pk_fma_f32 v[240:241], v[164:165], v[222:223], v[240:241]
	v_pk_fma_f32 v[238:239], v[166:167], v[216:217], v[238:239]
	v_pk_fma_f32 v[240:241], v[166:167], v[218:219], v[240:241]
	v_pk_mul_f32 v[242:243], v[176:177], v[238:239]
	v_pk_mul_f32 v[244:245], v[176:177], v[240:241]
	v_pk_mul_f32 v[242:243], v[238:239], v[242:243]
	v_pk_mul_f32 v[244:245], v[240:241], v[244:245]
	v_pk_fma_f32 v[242:243], v[238:239], v[242:243], v[238:239]
	v_pk_fma_f32 v[244:245], v[240:241], v[244:245], v[240:241]
	v_pk_mul_f32 v[242:243], v[178:179], v[242:243]
	v_pk_mul_f32 v[244:245], v[178:179], v[244:245]
	v_pk_add_f32 v[242:243], v[242:243], v[242:243]
	v_pk_add_f32 v[244:245], v[244:245], v[244:245]
	v_pk_mul_f32 v[242:243], v[180:181], v[242:243]
	v_pk_mul_f32 v[244:245], v[180:181], v[244:245]
	v_exp_f32_e32 v242, v242
	v_exp_f32_e32 v243, v243
	v_exp_f32_e32 v244, v244
	v_exp_f32_e32 v245, v245
	v_pk_add_f32 v[242:243], v[182:183], v[242:243]
	v_pk_add_f32 v[244:245], v[182:183], v[244:245]
	v_rcp_f32_e32 v242, v242
	v_rcp_f32_e32 v243, v243
	v_rcp_f32_e32 v244, v244
	v_rcp_f32_e32 v245, v245
	v_pk_mul_f32 v[238:239], v[238:239], v[242:243]
	v_pk_mul_f32 v[240:241], v[240:241], v[244:245]
	v_pk_mul_f32 v[8:9], v[8:9], v[238:239]
	v_pk_mul_f32 v[10:11], v[10:11], v[240:241]
	s_waitcnt lgkmcnt(0)
	v_mov_b32_e32 v232, v227
	v_mov_b32_e32 v233, v228
	v_mov_b32_e32 v234, v229
	v_mov_b32_e32 v235, v230
	v_mov_b32_e32 v236, v231
	v_pk_fma_f32 v[238:239], v[162:163], v[226:227], v[168:169]
	v_pk_fma_f32 v[240:241], v[162:163], v[228:229], v[168:169]
	v_pk_fma_f32 v[238:239], v[164:165], v[232:233], v[238:239]
	v_pk_fma_f32 v[240:241], v[164:165], v[234:235], v[240:241]
	v_pk_fma_f32 v[238:239], v[166:167], v[228:229], v[238:239]
	v_pk_fma_f32 v[240:241], v[166:167], v[230:231], v[240:241]
	v_pk_mul_f32 v[242:243], v[176:177], v[238:239]
	v_pk_mul_f32 v[244:245], v[176:177], v[240:241]
	v_pk_mul_f32 v[242:243], v[238:239], v[242:243]
	v_pk_mul_f32 v[244:245], v[240:241], v[244:245]
	v_pk_fma_f32 v[242:243], v[238:239], v[242:243], v[238:239]
	v_pk_fma_f32 v[244:245], v[240:241], v[244:245], v[240:241]
	v_pk_mul_f32 v[242:243], v[178:179], v[242:243]
	v_pk_mul_f32 v[244:245], v[178:179], v[244:245]
	v_pk_add_f32 v[242:243], v[242:243], v[242:243]
	v_pk_add_f32 v[244:245], v[244:245], v[244:245]
	v_pk_mul_f32 v[242:243], v[180:181], v[242:243]
	v_pk_mul_f32 v[244:245], v[180:181], v[244:245]
	v_exp_f32_e32 v242, v242
	v_exp_f32_e32 v243, v243
	v_exp_f32_e32 v244, v244
	v_exp_f32_e32 v245, v245
	v_pk_add_f32 v[242:243], v[182:183], v[242:243]
	v_pk_add_f32 v[244:245], v[182:183], v[244:245]
	v_rcp_f32_e32 v242, v242
	v_rcp_f32_e32 v243, v243
	v_rcp_f32_e32 v244, v244
	v_rcp_f32_e32 v245, v245
	v_pk_mul_f32 v[238:239], v[238:239], v[242:243]
	v_pk_mul_f32 v[240:241], v[240:241], v[244:245]
	v_pk_mul_f32 v[4:5], v[4:5], v[238:239]
	v_pk_mul_f32 v[6:7], v[6:7], v[240:241]
	s_waitcnt lgkmcnt(0)
	s_barrier
; template <bool ROPE>
; DI void img_put_bf16(const f32x4 (&acc)[8][4], char* smem, int rowoff, float scale, int prow0, const float* cosT) {
;   EPI_IDS;
;   u16* img = (u16*)smem + (wr * 128 + fq * 4 + rowoff) * IMG_LD + wc * 64 + fr;
; #pragma unroll
;   for (int m = 0; m < 8; ++m) {
;     float cs4[4] = {0.f, 0.f, 0.f, 0.f}, sn4[4] = {0.f, 0.f, 0.f, 0.f};
;     if (ROPE) {
; #pragma unroll
;       for (int j = 0; j < 4; ++j) { const int pos = prow0 + wr * 128 + m * 16 + fq * 4 + j; cs4[j] = cosT[pos * 8 + (fr & 7)]; sn4[j] = cosT[8192 * 8 + pos * 8 + (fr & 7)]; }
;     }
; #pragma unroll
;     for (int n = 0; n < 4; ++n)
; #pragma unroll
;       for (int j = 0; j < 4; ++j) img[(m * 16 + j) * IMG_LD + n * 16] = f2bf(epi_val<ROPE>(acc, m, n, j, cs4, sn4, fr) * scale);
;   }
	v_cvt_pk_bf16_f32 v1, v32, s0
	v_mov_b32_e32 v32, v33
	v_mov_b32_e32 v33, v34
	v_mov_b32_e32 v34, v35
	v_mov_b32_e32 v0, v7
	v_mov_b32_e32 v2, v184
	v_and_b32_e32 v7, 0xc0, v2
	v_and_b32_e32 v35, 15, v2
	v_lshrrev_b32_e32 v132, 1, v2
	v_lshrrev_b32_e32 v2, 2, v2
	v_and_b32_e32 v2, 12, v2
	v_and_or_b32 v2, v132, s5, v2
	v_mul_lo_u32 v2, v2, s3
	v_add_u32_e32 v2, 16, v2
	v_lshlrev_b32_e32 v7, 1, v7
	v_lshlrev_b32_e32 v35, 1, v35
	v_add3_u32 v2, v2, v7, v35
	ds_write_b16 v2, v1 offset:1152
	v_cvt_pk_bf16_f32 v1, v32, s0
	ds_write_b16 v2, v1 offset:1680
	v_cvt_pk_bf16_f32 v1, v33, s0
	ds_write_b16 v2, v1 offset:2208
	v_cvt_pk_bf16_f32 v1, v34, s0
	ds_write_b16 v2, v1 offset:2736
	v_cvt_pk_bf16_f32 v1, v124, s0
	ds_write_b16 v2, v1 offset:9504
	v_cvt_pk_bf16_f32 v1, v125, s0
	ds_write_b16 v2, v1 offset:10032
	v_cvt_pk_bf16_f32 v1, v126, s0
	ds_write_b16 v2, v1 offset:10560
	v_cvt_pk_bf16_f32 v1, v127, s0
	ds_write_b16 v2, v1 offset:11088
	v_cvt_pk_bf16_f32 v1, v92, s0
	ds_write_b16 v2, v1 offset:9536
	v_cvt_pk_bf16_f32 v1, v93, s0
	ds_write_b16 v2, v1 offset:10064
	v_cvt_pk_bf16_f32 v1, v94, s0
	ds_write_b16 v2, v1 offset:10592
	v_cvt_pk_bf16_f32 v1, v95, s0
	ds_write_b16 v2, v1 offset:11120
	v_cvt_pk_bf16_f32 v1, v60, s0
	ds_write_b16 v2, v1 offset:9568
	v_cvt_pk_bf16_f32 v1, v61, s0
	ds_write_b16 v2, v1 offset:10096
	v_cvt_pk_bf16_f32 v1, v62, s0
	ds_write_b16 v2, v1 offset:10624
	v_cvt_pk_bf16_f32 v1, v63, s0
	ds_write_b16 v2, v1 offset:11152
	v_cvt_pk_bf16_f32 v1, v28, s0
	ds_write_b16 v2, v1 offset:9600
	v_cvt_pk_bf16_f32 v1, v29, s0
	ds_write_b16 v2, v1 offset:10128
	v_cvt_pk_bf16_f32 v1, v30, s0
	ds_write_b16 v2, v1 offset:10656
	v_cvt_pk_bf16_f32 v1, v31, s0
	ds_write_b16 v2, v1 offset:11184
	v_cvt_pk_bf16_f32 v1, v120, s0
	ds_write_b16 v2, v1 offset:17952
	v_cvt_pk_bf16_f32 v1, v121, s0
	ds_write_b16 v2, v1 offset:18480
	v_cvt_pk_bf16_f32 v1, v122, s0
	ds_write_b16 v2, v1 offset:19008
	v_cvt_pk_bf16_f32 v1, v123, s0
	ds_write_b16 v2, v1 offset:19536
	v_cvt_pk_bf16_f32 v1, v88, s0
	ds_write_b16 v2, v1 offset:17984
	v_cvt_pk_bf16_f32 v1, v89, s0
	ds_write_b16 v2, v1 offset:18512
	v_cvt_pk_bf16_f32 v1, v90, s0
	ds_write_b16 v2, v1 offset:19040
	v_cvt_pk_bf16_f32 v1, v91, s0
	ds_write_b16 v2, v1 offset:19568
	v_cvt_pk_bf16_f32 v1, v56, s0
	ds_write_b16 v2, v1 offset:18016
	v_cvt_pk_bf16_f32 v1, v57, s0
	ds_write_b16 v2, v1 offset:18544
	v_cvt_pk_bf16_f32 v1, v58, s0
	ds_write_b16 v2, v1 offset:19072
	v_cvt_pk_bf16_f32 v1, v59, s0
	ds_write_b16 v2, v1 offset:19600
	v_cvt_pk_bf16_f32 v1, v24, s0
	ds_write_b16 v2, v1 offset:18048
	v_cvt_pk_bf16_f32 v1, v25, s0
	ds_write_b16 v2, v1 offset:18576
	v_cvt_pk_bf16_f32 v1, v26, s0
	ds_write_b16 v2, v1 offset:19104
	v_cvt_pk_bf16_f32 v1, v27, s0
	ds_write_b16 v2, v1 offset:19632
	v_cvt_pk_bf16_f32 v1, v116, s0
	ds_write_b16 v2, v1 offset:26400
	v_cvt_pk_bf16_f32 v1, v117, s0
	ds_write_b16 v2, v1 offset:26928
	v_cvt_pk_bf16_f32 v1, v118, s0
	ds_write_b16 v2, v1 offset:27456
	v_cvt_pk_bf16_f32 v1, v119, s0
	ds_write_b16 v2, v1 offset:27984
	v_cvt_pk_bf16_f32 v1, v84, s0
	ds_write_b16 v2, v1 offset:26432
	v_cvt_pk_bf16_f32 v1, v85, s0
	ds_write_b16 v2, v1 offset:26960
	v_cvt_pk_bf16_f32 v1, v86, s0
	ds_write_b16 v2, v1 offset:27488
	v_cvt_pk_bf16_f32 v1, v87, s0
	ds_write_b16 v2, v1 offset:28016
	v_cvt_pk_bf16_f32 v1, v52, s0
	ds_write_b16 v2, v1 offset:26464
	v_cvt_pk_bf16_f32 v1, v53, s0
	ds_write_b16 v2, v1 offset:26992
	v_cvt_pk_bf16_f32 v1, v54, s0
	ds_write_b16 v2, v1 offset:27520
	v_cvt_pk_bf16_f32 v1, v55, s0
	ds_write_b16 v2, v1 offset:28048
	v_cvt_pk_bf16_f32 v1, v20, s0
	ds_write_b16 v2, v1 offset:26496
	v_cvt_pk_bf16_f32 v1, v21, s0
	ds_write_b16 v2, v1 offset:27024
	v_cvt_pk_bf16_f32 v1, v22, s0
	ds_write_b16 v2, v1 offset:27552
	v_cvt_pk_bf16_f32 v1, v23, s0
	ds_write_b16 v2, v1 offset:28080
	v_cvt_pk_bf16_f32 v1, v112, s0
	ds_write_b16 v2, v1 offset:34848
	v_cvt_pk_bf16_f32 v1, v113, s0
	ds_write_b16 v2, v1 offset:35376
	v_cvt_pk_bf16_f32 v1, v114, s0
	ds_write_b16 v2, v1 offset:35904
	v_cvt_pk_bf16_f32 v1, v115, s0
	ds_write_b16 v2, v1 offset:36432
	v_cvt_pk_bf16_f32 v1, v80, s0
	ds_write_b16 v2, v1 offset:34880
	v_cvt_pk_bf16_f32 v1, v81, s0
	ds_write_b16 v2, v1 offset:35408
	v_cvt_pk_bf16_f32 v1, v82, s0
	ds_write_b16 v2, v1 offset:35936
	v_cvt_pk_bf16_f32 v1, v83, s0
	ds_write_b16 v2, v1 offset:36464
	v_cvt_pk_bf16_f32 v1, v48, s0
	ds_write_b16 v2, v1 offset:34912
	v_cvt_pk_bf16_f32 v1, v49, s0
	ds_write_b16 v2, v1 offset:35440
	v_cvt_pk_bf16_f32 v1, v50, s0
	ds_write_b16 v2, v1 offset:35968
	v_cvt_pk_bf16_f32 v1, v51, s0
	ds_write_b16 v2, v1 offset:36496
	v_cvt_pk_bf16_f32 v1, v16, s0
	ds_write_b16 v2, v1 offset:34944
	v_cvt_pk_bf16_f32 v1, v17, s0
	ds_write_b16 v2, v1 offset:35472
	v_cvt_pk_bf16_f32 v1, v18, s0
	ds_write_b16 v2, v1 offset:36000
	v_cvt_pk_bf16_f32 v1, v19, s0
	ds_write_b16 v2, v1 offset:36528
	v_cvt_pk_bf16_f32 v1, v108, s0
	ds_write_b16 v2, v1 offset:43296
	v_cvt_pk_bf16_f32 v1, v109, s0
	ds_write_b16 v2, v1 offset:43824
	v_cvt_pk_bf16_f32 v1, v110, s0
	ds_write_b16 v2, v1 offset:44352
	v_cvt_pk_bf16_f32 v1, v111, s0
	ds_write_b16 v2, v1 offset:44880
	v_cvt_pk_bf16_f32 v1, v76, s0
	ds_write_b16 v2, v1 offset:43328
	v_cvt_pk_bf16_f32 v1, v77, s0
	ds_write_b16 v2, v1 offset:43856
	v_cvt_pk_bf16_f32 v1, v78, s0
	ds_write_b16 v2, v1 offset:44384
	v_cvt_pk_bf16_f32 v1, v79, s0
	ds_write_b16 v2, v1 offset:44912
	v_cvt_pk_bf16_f32 v1, v44, s0
	ds_write_b16 v2, v1 offset:43360
	v_cvt_pk_bf16_f32 v1, v45, s0
	ds_write_b16 v2, v1 offset:43888
	v_cvt_pk_bf16_f32 v1, v46, s0
	ds_write_b16 v2, v1 offset:44416
	v_cvt_pk_bf16_f32 v1, v47, s0
	ds_write_b16 v2, v1 offset:44944
; template <bool ROPE>
; DI void img_put_bf16(const f32x4 (&acc)[8][4], char* smem, int rowoff, float scale, int prow0, const float* cosT) {
;   EPI_IDS;
;   u16* img = (u16*)smem + (wr * 128 + fq * 4 + rowoff) * IMG_LD + wc * 64 + fr;
; #pragma unroll
;   for (int m = 0; m < 8; ++m) {
;     float cs4[4] = {0.f, 0.f, 0.f, 0.f}, sn4[4] = {0.f, 0.f, 0.f, 0.f};
;     if (ROPE) {
; #pragma unroll
;       for (int j = 0; j < 4; ++j) { const int pos = prow0 + wr * 128 + m * 16 + fq * 4 + j; cs4[j] = cosT[pos * 8 + (fr & 7)]; sn4[j] = cosT[8192 * 8 + pos * 8 + (fr & 7)]; }
;     }
; #pragma unroll
;     for (int n = 0; n < 4; ++n)
; #pragma unroll
;       for (int j = 0; j < 4; ++j) img[(m * 16 + j) * IMG_LD + n * 16] = f2bf(epi_val<ROPE>(acc, m, n, j, cs4, sn4, fr) * scale);
;   }
	v_cvt_pk_bf16_f32 v1, v12, s0
	ds_write_b16 v2, v1 offset:43392
	v_cvt_pk_bf16_f32 v1, v13, s0
	ds_write_b16 v2, v1 offset:43920
	v_cvt_pk_bf16_f32 v1, v14, s0
	ds_write_b16 v2, v1 offset:44448
	v_cvt_pk_bf16_f32 v1, v15, s0
	ds_write_b16 v2, v1 offset:44976
	v_cvt_pk_bf16_f32 v1, v104, s0
	ds_write_b16 v2, v1 offset:51744
	v_cvt_pk_bf16_f32 v1, v105, s0
	ds_write_b16 v2, v1 offset:52272
	v_cvt_pk_bf16_f32 v1, v106, s0
	ds_write_b16 v2, v1 offset:52800
	v_cvt_pk_bf16_f32 v1, v107, s0
	ds_write_b16 v2, v1 offset:53328
	v_cvt_pk_bf16_f32 v1, v72, s0
	ds_write_b16 v2, v1 offset:51776
	v_cvt_pk_bf16_f32 v1, v73, s0
	ds_write_b16 v2, v1 offset:52304
	v_cvt_pk_bf16_f32 v1, v74, s0
	ds_write_b16 v2, v1 offset:52832
	v_cvt_pk_bf16_f32 v1, v75, s0
	ds_write_b16 v2, v1 offset:53360
	v_cvt_pk_bf16_f32 v1, v40, s0
	ds_write_b16 v2, v1 offset:51808
	v_cvt_pk_bf16_f32 v1, v41, s0
	ds_write_b16 v2, v1 offset:52336
	v_cvt_pk_bf16_f32 v1, v42, s0
	ds_write_b16 v2, v1 offset:52864
	v_cvt_pk_bf16_f32 v1, v43, s0
	ds_write_b16 v2, v1 offset:53392
	v_cvt_pk_bf16_f32 v1, v8, s0
	ds_write_b16 v2, v1 offset:51840
	v_cvt_pk_bf16_f32 v1, v9, s0
	ds_write_b16 v2, v1 offset:52368
	v_cvt_pk_bf16_f32 v1, v10, s0
	ds_write_b16 v2, v1 offset:52896
	v_cvt_pk_bf16_f32 v1, v11, s0
	ds_write_b16 v2, v1 offset:53424
	v_cvt_pk_bf16_f32 v1, v100, s0
	ds_write_b16 v2, v1 offset:60192
	v_cvt_pk_bf16_f32 v1, v101, s0
	ds_write_b16 v2, v1 offset:60720
	v_cvt_pk_bf16_f32 v1, v102, s0
	v_cvt_pk_bf16_f32 v7, v128, s0
	ds_write_b16 v2, v1 offset:61248
	v_cvt_pk_bf16_f32 v1, v103, s0
	ds_write_b16 v2, v7 offset:1056
	v_cvt_pk_bf16_f32 v7, v129, s0
	ds_write_b16 v2, v1 offset:61776
	v_cvt_pk_bf16_f32 v1, v68, s0
	ds_write_b16 v2, v7 offset:1584
	v_cvt_pk_bf16_f32 v7, v130, s0
	ds_write_b16 v2, v1 offset:60224
	v_cvt_pk_bf16_f32 v1, v69, s0
	ds_write_b16 v2, v7 offset:2112
	v_cvt_pk_bf16_f32 v7, v131, s0
	ds_write_b16 v2, v1 offset:60752
	v_cvt_pk_bf16_f32 v1, v70, s0
	ds_write_b16 v2, v7 offset:2640
	v_cvt_pk_bf16_f32 v7, v96, s0
	ds_write_b16 v2, v1 offset:61280
	v_cvt_pk_bf16_f32 v1, v71, s0
	ds_write_b16 v2, v7 offset:1088
	v_cvt_pk_bf16_f32 v7, v97, s0
	ds_write_b16 v2, v1 offset:61808
	v_cvt_pk_bf16_f32 v1, v36, s0
	ds_write_b16 v2, v7 offset:1616
	v_cvt_pk_bf16_f32 v7, v98, s0
	ds_write_b16 v2, v1 offset:60256
	v_cvt_pk_bf16_f32 v1, v37, s0
	ds_write_b16 v2, v7 offset:2144
	v_cvt_pk_bf16_f32 v7, v99, s0
	ds_write_b16 v2, v1 offset:60784
	v_cvt_pk_bf16_f32 v1, v38, s0
	ds_write_b16 v2, v7 offset:2672
	v_cvt_pk_bf16_f32 v7, v64, s0
	ds_write_b16 v2, v1 offset:61312
	v_cvt_pk_bf16_f32 v1, v39, s0
	ds_write_b16 v2, v7 offset:1120
	v_cvt_pk_bf16_f32 v7, v65, s0
	ds_write_b16 v2, v1 offset:61840
	v_cvt_pk_bf16_f32 v1, v4, s0
	ds_write_b16 v2, v7 offset:1648
	v_cvt_pk_bf16_f32 v7, v66, s0
	ds_write_b16 v2, v1 offset:60288
	v_cvt_pk_bf16_f32 v1, v5, s0
	ds_write_b16 v2, v7 offset:2176
	v_cvt_pk_bf16_f32 v7, v67, s0
	ds_write_b16 v2, v1 offset:60816
	v_cvt_pk_bf16_f32 v1, v6, s0
	v_cvt_pk_bf16_f32 v0, v0, s0
	ds_write_b16 v2, v7 offset:2704
	ds_write_b16 v2, v1 offset:61344
	ds_write_b16 v2, v0 offset:61872
	v_mov_b32_e32 v1, v184
	s_waitcnt lgkmcnt(0)
	s_barrier
; DI int TID512() { int t = threadIdx.x; asm volatile("" : "+v"(t)); return t; }
; DI void img_store_bf16(u16* dst, int ld, const char* smem, int rowoff) {
;   const int tid = TID512();
; #pragma unroll
;   for (int q = 0; q < 16; ++q) {
;     const int slot = tid + q * 512, row = slot >> 5, c16 = slot & 31;
;     *(u32x4*)(dst + (size_t)row * ld + c16 * 8) = *(const u32x4*)(smem + (row + rowoff) * (IMG_LD * 2) + c16 * 16);
;   }
; }
	s_addc_u32 s5, s77, s39
	s_add_u32 s4, s4, s48
	v_lshlrev_b32_e32 v0, 4, v1
	v_and_b32_e32 v172, 0x1f0, v0
	s_addc_u32 s5, s5, s49
	v_add_u32_e32 v0, 16, v172
	v_ashrrev_i32_e32 v2, 5, v1
	v_lshl_add_u64 v[8:9], s[4:5], 0, v[172:173]
	v_mad_u64_u32 v[4:5], s[4:5], v2, s3, v[0:1]
	ds_read_b128 v[4:7], v4 offset:1056
	v_mad_i64_i32 v[10:11], s[4:5], v2, s96, v[8:9]
	v_add_u32_e32 v2, 0x200, v1
	v_ashrrev_i32_e32 v2, 5, v2
	s_waitcnt lgkmcnt(0)
	global_store_dwordx4 v[10:11], v[4:7], off
	v_mad_i64_i32 v[10:11], s[4:5], v2, s96, v[8:9]
	s_nop 0
	v_mad_u64_u32 v[4:5], s[4:5], v2, s3, v[0:1]
	ds_read_b128 v[4:7], v4 offset:1056
	v_add_u32_e32 v2, 0x400, v1
	v_ashrrev_i32_e32 v2, 5, v2
	s_waitcnt lgkmcnt(0)
	global_store_dwordx4 v[10:11], v[4:7], off
	s_nop 1
	v_mad_u64_u32 v[4:5], s[4:5], v2, s3, v[0:1]
	ds_read_b128 v[4:7], v4 offset:1056
	v_mad_i64_i32 v[10:11], s[4:5], v2, s96, v[8:9]
	v_add_u32_e32 v2, 0x600, v1
	v_ashrrev_i32_e32 v2, 5, v2
	s_waitcnt lgkmcnt(0)
	global_store_dwordx4 v[10:11], v[4:7], off
	v_mad_i64_i32 v[10:11], s[4:5], v2, s96, v[8:9]
	s_nop 0
	v_mad_u64_u32 v[4:5], s[4:5], v2, s3, v[0:1]
	ds_read_b128 v[4:7], v4 offset:1056
	v_add_u32_e32 v2, 0x800, v1
	v_ashrrev_i32_e32 v2, 5, v2
	s_waitcnt lgkmcnt(0)
	global_store_dwordx4 v[10:11], v[4:7], off
	s_nop 1
	v_mad_u64_u32 v[4:5], s[4:5], v2, s3, v[0:1]
	ds_read_b128 v[4:7], v4 offset:1056
	v_mad_i64_i32 v[10:11], s[4:5], v2, s96, v[8:9]
	v_add_u32_e32 v2, 0xa00, v1
	v_ashrrev_i32_e32 v2, 5, v2
	s_waitcnt lgkmcnt(0)
	global_store_dwordx4 v[10:11], v[4:7], off
	v_mad_i64_i32 v[10:11], s[4:5], v2, s96, v[8:9]
	s_nop 0
	v_mad_u64_u32 v[4:5], s[4:5], v2, s3, v[0:1]
	ds_read_b128 v[4:7], v4 offset:1056
	v_add_u32_e32 v2, 0xc00, v1
	v_ashrrev_i32_e32 v2, 5, v2
	s_waitcnt lgkmcnt(0)
	global_store_dwordx4 v[10:11], v[4:7], off
	s_nop 1
	v_mad_u64_u32 v[4:5], s[4:5], v2, s3, v[0:1]
	ds_read_b128 v[4:7], v4 offset:1056
	v_mad_i64_i32 v[10:11], s[4:5], v2, s96, v[8:9]
	v_add_u32_e32 v2, 0xe00, v1
	v_ashrrev_i32_e32 v2, 5, v2
	s_waitcnt lgkmcnt(0)
	global_store_dwordx4 v[10:11], v[4:7], off
	v_mad_i64_i32 v[10:11], s[4:5], v2, s96, v[8:9]
	s_nop 0
	v_mad_u64_u32 v[4:5], s[4:5], v2, s3, v[0:1]
	ds_read_b128 v[4:7], v4 offset:1056
	v_add_u32_e32 v2, 0x1000, v1
	v_ashrrev_i32_e32 v2, 5, v2
	s_waitcnt lgkmcnt(0)
	global_store_dwordx4 v[10:11], v[4:7], off
	s_nop 1
	v_mad_u64_u32 v[4:5], s[4:5], v2, s3, v[0:1]
	ds_read_b128 v[4:7], v4 offset:1056
	v_mad_i64_i32 v[10:11], s[4:5], v2, s96, v[8:9]
	v_add_u32_e32 v2, 0x1200, v1
	v_ashrrev_i32_e32 v2, 5, v2
	s_waitcnt lgkmcnt(0)
	global_store_dwordx4 v[10:11], v[4:7], off
	v_mad_i64_i32 v[10:11], s[4:5], v2, s96, v[8:9]
	s_nop 0
	v_mad_u64_u32 v[4:5], s[4:5], v2, s3, v[0:1]
	ds_read_b128 v[4:7], v4 offset:1056
	v_add_u32_e32 v2, 0x1400, v1
	v_ashrrev_i32_e32 v2, 5, v2
	s_waitcnt lgkmcnt(0)
	global_store_dwordx4 v[10:11], v[4:7], off
	s_nop 1
	v_mad_u64_u32 v[4:5], s[4:5], v2, s3, v[0:1]
	ds_read_b128 v[4:7], v4 offset:1056
	v_mad_i64_i32 v[10:11], s[4:5], v2, s96, v[8:9]
	v_add_u32_e32 v2, 0x1600, v1
	v_ashrrev_i32_e32 v2, 5, v2
	s_waitcnt lgkmcnt(0)
	global_store_dwordx4 v[10:11], v[4:7], off
	v_mad_i64_i32 v[10:11], s[4:5], v2, s96, v[8:9]
	s_nop 0
	v_mad_u64_u32 v[4:5], s[4:5], v2, s3, v[0:1]
	ds_read_b128 v[4:7], v4 offset:1056
	v_add_u32_e32 v2, 0x1800, v1
	v_ashrrev_i32_e32 v2, 5, v2
	s_waitcnt lgkmcnt(0)
	global_store_dwordx4 v[10:11], v[4:7], off
	s_nop 1
	v_mad_u64_u32 v[4:5], s[4:5], v2, s3, v[0:1]
	ds_read_b128 v[4:7], v4 offset:1056
	v_mad_i64_i32 v[10:11], s[4:5], v2, s96, v[8:9]
	v_add_u32_e32 v2, 0x1a00, v1
	v_ashrrev_i32_e32 v2, 5, v2
	s_waitcnt lgkmcnt(0)
	global_store_dwordx4 v[10:11], v[4:7], off
	v_mad_i64_i32 v[10:11], s[4:5], v2, s96, v[8:9]
	s_nop 0
	v_mad_u64_u32 v[4:5], s[4:5], v2, s3, v[0:1]
	ds_read_b128 v[4:7], v4 offset:1056
	v_add_u32_e32 v2, 0x1c00, v1
	v_ashrrev_i32_e32 v2, 5, v2
	s_waitcnt lgkmcnt(0)
	global_store_dwordx4 v[10:11], v[4:7], off
	s_nop 1
	v_mad_u64_u32 v[4:5], s[4:5], v2, s3, v[0:1]
	ds_read_b128 v[4:7], v4 offset:1056
	v_add_u32_e32 v1, 0x1e00, v1
	v_mad_i64_i32 v[10:11], s[4:5], v2, s96, v[8:9]
	v_ashrrev_i32_e32 v2, 5, v1
	v_mad_u64_u32 v[0:1], s[4:5], v2, s3, v[0:1]
	s_waitcnt lgkmcnt(0)
	global_store_dwordx4 v[10:11], v[4:7], off
	ds_read_b128 v[4:7], v0 offset:1056
	v_mad_i64_i32 v[0:1], s[4:5], v2, s96, v[8:9]
	s_waitcnt lgkmcnt(0)
	global_store_dwordx4 v[0:1], v[4:7], off
